# back-edge rotation: K-loop counter/exit-test SALU moved in front of the closing barrier (5 GEMM loops)
# baseline (speedup 1.0000x reference)
.LBB0_383:
	s_ashr_i32 s67, s66, 31
	s_lshl_b64 s[26:27], s[66:67], 19
	s_add_u32 s26, s40, s26
	s_addc_u32 s27, s41, s27
	s_and_b64 s[34:35], s[8:9], exec
	s_cselect_b32 s34, s27, s5
	s_cselect_b32 s35, s26, s4
	s_ashr_i32 s29, s28, 31
	s_lshl_b64 s[38:39], s[28:29], 19
	s_add_u32 s62, s10, s38
	s_addc_u32 s63, s11, s39
	s_and_b64 s[38:39], s[8:9], exec
	s_cselect_b32 s29, s63, s83
	s_cselect_b32 s38, s62, s82
	s_add_u32 s39, s82, 0x100
	s_addc_u32 s67, s83, 0
	s_mov_b32 s94, -2
	s_mov_b64 vcc, 0
	v_lshl_add_u64 v[132:133], s[4:5], 0, v[168:169]
	ds_read_b128 v[134:137], v199
	ds_read_b128 v[138:141], v200
	ds_read_b128 v[142:145], v201
	ds_read_b128 v[146:149], v202
	ds_read_b128 v[150:153], v203
	ds_read_b128 v[174:177], v204
	ds_read_b128 v[178:181], v205
	ds_read_b128 v[182:185], v206
	s_add_u32 s24, s4, vcc_lo
	s_addc_u32 s25, s5, vcc_hi
	s_add_u32 s24, s24, 0x100
	s_addc_u32 s25, s25, 0
	s_add_u32 s82, s39, vcc_lo
	s_addc_u32 s83, s67, vcc_hi
	s_cmpk_eq_i32 vcc_lo, 0x700
	s_cselect_b32 s87, s29, s83
	s_cselect_b32 s86, s38, s82
	s_cselect_b32 s83, s34, s25
	s_cselect_b32 s82, s35, s24
	v_lshl_add_u64 v[154:155], v[132:133], 0, vcc
	v_lshl_add_u64 v[250:251], v[154:155], 0, s[48:49]
	s_add_i32 m0, s79, 0x8000
	s_mov_b64 s[24:25], 0x20080
	ds_read_b128 v[218:221], v207
	ds_read_b128 v[222:225], v207 offset:2048
	ds_read_b128 v[226:229], v208
	ds_read_b128 v[230:233], v208 offset:2048
	ds_read_b128 v[234:237], v207 offset:4096
	ds_read_b128 v[238:241], v207 offset:6144
	ds_read_b128 v[242:245], v208 offset:4096
	ds_read_b128 v[246:249], v208 offset:6144
	global_load_lds_dwordx4 v[250:251], off
	v_lshl_add_u64 v[250:251], v[154:155], 0, s[24:25]
	s_add_i32 m0, s79, 0xa000
	s_mov_b64 s[24:25], 0x60080
	global_load_lds_dwordx4 v[250:251], off
	v_lshl_add_u64 v[250:251], v[154:155], 0, s[50:51]
	s_add_i32 m0, s79, 0xc000
	v_lshl_add_u64 v[154:155], v[154:155], 0, s[24:25]
	global_load_lds_dwordx4 v[250:251], off
	s_add_i32 m0, s79, 0xe000
	s_nop 0
	global_load_lds_dwordx4 v[154:155], off
	s_waitcnt lgkmcnt(0)
	s_barrier
	v_mfma_f32_16x16x32_bf16 v[128:131], v[134:137], v[218:221], 0
	v_mfma_f32_16x16x32_bf16 v[124:127], v[142:145], v[218:221], 0
	v_mfma_f32_16x16x32_bf16 v[112:115], v[134:137], v[222:225], 0
	v_mfma_f32_16x16x32_bf16 v[108:111], v[142:145], v[222:225], 0
	v_mfma_f32_16x16x32_bf16 v[96:99], v[134:137], v[234:237], 0
	v_mfma_f32_16x16x32_bf16 v[92:95], v[142:145], v[234:237], 0
	v_mfma_f32_16x16x32_bf16 v[80:83], v[134:137], v[238:241], 0
	v_mfma_f32_16x16x32_bf16 v[76:79], v[142:145], v[238:241], 0
	v_mfma_f32_16x16x32_bf16 v[128:131], v[138:141], v[226:229], v[128:131]
	v_mfma_f32_16x16x32_bf16 v[124:127], v[146:149], v[226:229], v[124:127]
	v_mfma_f32_16x16x32_bf16 v[112:115], v[138:141], v[230:233], v[112:115]
	v_mfma_f32_16x16x32_bf16 v[108:111], v[146:149], v[230:233], v[108:111]
	v_mfma_f32_16x16x32_bf16 v[96:99], v[138:141], v[242:245], v[96:99]
	v_mfma_f32_16x16x32_bf16 v[92:95], v[146:149], v[242:245], v[92:95]
	v_mfma_f32_16x16x32_bf16 v[80:83], v[138:141], v[246:249], v[80:83]
	v_mfma_f32_16x16x32_bf16 v[76:79], v[146:149], v[246:249], v[76:79]
	v_mfma_f32_16x16x32_bf16 v[120:123], v[150:153], v[218:221], 0
	v_mfma_f32_16x16x32_bf16 v[116:119], v[178:181], v[218:221], 0
	v_mfma_f32_16x16x32_bf16 v[104:107], v[150:153], v[222:225], 0
	v_mfma_f32_16x16x32_bf16 v[100:103], v[178:181], v[222:225], 0
	v_mfma_f32_16x16x32_bf16 v[88:91], v[150:153], v[234:237], 0
	v_mfma_f32_16x16x32_bf16 v[84:87], v[178:181], v[234:237], 0
	v_mfma_f32_16x16x32_bf16 v[72:75], v[150:153], v[238:241], 0
	v_mfma_f32_16x16x32_bf16 v[68:71], v[178:181], v[238:241], 0
	v_mfma_f32_16x16x32_bf16 v[120:123], v[174:177], v[226:229], v[120:123]
	v_mfma_f32_16x16x32_bf16 v[116:119], v[182:185], v[226:229], v[116:119]
	v_mfma_f32_16x16x32_bf16 v[104:107], v[174:177], v[230:233], v[104:107]
	v_mfma_f32_16x16x32_bf16 v[100:103], v[182:185], v[230:233], v[100:103]
	v_mfma_f32_16x16x32_bf16 v[88:91], v[174:177], v[242:245], v[88:91]
	v_mfma_f32_16x16x32_bf16 v[84:87], v[182:185], v[242:245], v[84:87]
	v_mfma_f32_16x16x32_bf16 v[72:75], v[174:177], v[246:249], v[72:75]
	v_mfma_f32_16x16x32_bf16 v[68:71], v[182:185], v[246:249], v[68:71]
	s_barrier
	s_add_i32 s24, s1, s77
	v_lshl_add_u64 v[154:155], s[86:87], 0, v[158:159]
	s_mov_b32 m0, s24
	ds_read_b128 v[218:221], v207 offset:16384
	ds_read_b128 v[222:225], v207 offset:18432
	ds_read_b128 v[226:229], v208 offset:16384
	ds_read_b128 v[230:233], v208 offset:18432
	ds_read_b128 v[234:237], v207 offset:20480
	ds_read_b128 v[238:241], v207 offset:22528
	ds_read_b128 v[242:245], v208 offset:20480
	ds_read_b128 v[246:249], v208 offset:22528
	global_load_lds_dwordx4 v[154:155], off
	v_lshl_add_u64 v[250:251], v[154:155], 0, s[14:15]
	s_add_i32 m0, s24, 0x2000
	s_add_i32 s24, s12, s77
	global_load_lds_dwordx4 v[250:251], off
	v_lshl_add_u64 v[250:251], v[154:155], 0, s[16:17]
	s_mov_b32 m0, s24
	s_nop 0
	global_load_lds_dwordx4 v[250:251], off
	v_lshl_add_u64 v[250:251], v[154:155], 0, s[18:19]
	s_add_i32 m0, s24, 0x2000
	s_nop 0
	global_load_lds_dwordx4 v[250:251], off
	s_waitcnt vmcnt(4)
	s_waitcnt lgkmcnt(0)
	s_barrier
	v_mfma_f32_16x16x32_bf16 v[64:67], v[134:137], v[218:221], 0
	v_mfma_f32_16x16x32_bf16 v[60:63], v[142:145], v[218:221], 0
	v_mfma_f32_16x16x32_bf16 v[48:51], v[134:137], v[222:225], 0
	v_mfma_f32_16x16x32_bf16 v[44:47], v[142:145], v[222:225], 0
	v_mfma_f32_16x16x32_bf16 v[32:35], v[134:137], v[234:237], 0
	v_mfma_f32_16x16x32_bf16 v[28:31], v[142:145], v[234:237], 0
	v_mfma_f32_16x16x32_bf16 v[16:19], v[134:137], v[238:241], 0
	v_mfma_f32_16x16x32_bf16 v[12:15], v[142:145], v[238:241], 0
	v_mfma_f32_16x16x32_bf16 v[64:67], v[138:141], v[226:229], v[64:67]
	v_mfma_f32_16x16x32_bf16 v[60:63], v[146:149], v[226:229], v[60:63]
	v_mfma_f32_16x16x32_bf16 v[48:51], v[138:141], v[230:233], v[48:51]
	v_mfma_f32_16x16x32_bf16 v[44:47], v[146:149], v[230:233], v[44:47]
	v_mfma_f32_16x16x32_bf16 v[32:35], v[138:141], v[242:245], v[32:35]
	v_mfma_f32_16x16x32_bf16 v[28:31], v[146:149], v[242:245], v[28:31]
	v_mfma_f32_16x16x32_bf16 v[16:19], v[138:141], v[246:249], v[16:19]
	v_mfma_f32_16x16x32_bf16 v[12:15], v[146:149], v[246:249], v[12:15]
	v_mfma_f32_16x16x32_bf16 v[56:59], v[150:153], v[218:221], 0
	v_mfma_f32_16x16x32_bf16 v[52:55], v[178:181], v[218:221], 0
	v_mfma_f32_16x16x32_bf16 v[40:43], v[150:153], v[222:225], 0
	v_mfma_f32_16x16x32_bf16 v[36:39], v[178:181], v[222:225], 0
	v_mfma_f32_16x16x32_bf16 v[24:27], v[150:153], v[234:237], 0
	v_mfma_f32_16x16x32_bf16 v[20:23], v[178:181], v[234:237], 0
	v_mfma_f32_16x16x32_bf16 v[8:11], v[150:153], v[238:241], 0
	v_mfma_f32_16x16x32_bf16 v[4:7], v[178:181], v[238:241], 0
	v_mfma_f32_16x16x32_bf16 v[56:59], v[174:177], v[226:229], v[56:59]
	v_mfma_f32_16x16x32_bf16 v[52:55], v[182:185], v[226:229], v[52:55]
	v_mfma_f32_16x16x32_bf16 v[40:43], v[174:177], v[230:233], v[40:43]
	v_mfma_f32_16x16x32_bf16 v[36:39], v[182:185], v[230:233], v[36:39]
	v_mfma_f32_16x16x32_bf16 v[24:27], v[174:177], v[242:245], v[24:27]
	v_mfma_f32_16x16x32_bf16 v[20:23], v[182:185], v[242:245], v[20:23]
	v_mfma_f32_16x16x32_bf16 v[8:11], v[174:177], v[246:249], v[8:11]
	v_mfma_f32_16x16x32_bf16 v[4:7], v[182:185], v[246:249], v[4:7]
	s_barrier
	ds_read_b128 v[134:137], v213
	ds_read_b128 v[138:141], v214
	ds_read_b128 v[142:145], v209
	ds_read_b128 v[146:149], v210
	ds_read_b128 v[150:153], v215
	ds_read_b128 v[174:177], v216
	ds_read_b128 v[178:181], v211
	ds_read_b128 v[182:185], v212
	s_mov_b32 m0, s79
	v_lshl_add_u64 v[250:251], s[82:83], 0, v[0:1]
	ds_read_b128 v[218:221], v207 offset:32768
	ds_read_b128 v[222:225], v207 offset:34816
	ds_read_b128 v[226:229], v208 offset:32768
	ds_read_b128 v[230:233], v208 offset:34816
	ds_read_b128 v[234:237], v207 offset:36864
	ds_read_b128 v[238:241], v207 offset:38912
	ds_read_b128 v[242:245], v208 offset:36864
	ds_read_b128 v[246:249], v208 offset:38912
	global_load_lds_dwordx4 v[250:251], off
	v_lshl_add_u64 v[252:253], v[250:251], 0, s[20:21]
	s_mov_b32 m0, s81
	s_nop 0
	global_load_lds_dwordx4 v[252:253], off
	v_lshl_add_u64 v[252:253], v[250:251], 0, s[14:15]
	s_mov_b32 m0, s97
	v_lshl_add_u64 v[250:251], v[250:251], 0, s[22:23]
	global_load_lds_dwordx4 v[252:253], off
	s_mov_b32 m0, s64
	s_nop 0
	global_load_lds_dwordx4 v[250:251], off
	s_waitcnt vmcnt(8)
	s_waitcnt lgkmcnt(0)
	s_barrier
	v_mfma_f32_16x16x32_bf16 v[128:131], v[134:137], v[218:221], v[128:131]
	v_mfma_f32_16x16x32_bf16 v[124:127], v[142:145], v[218:221], v[124:127]
	v_mfma_f32_16x16x32_bf16 v[112:115], v[134:137], v[222:225], v[112:115]
	v_mfma_f32_16x16x32_bf16 v[108:111], v[142:145], v[222:225], v[108:111]
	v_mfma_f32_16x16x32_bf16 v[96:99], v[134:137], v[234:237], v[96:99]
	v_mfma_f32_16x16x32_bf16 v[92:95], v[142:145], v[234:237], v[92:95]
	v_mfma_f32_16x16x32_bf16 v[80:83], v[134:137], v[238:241], v[80:83]
	v_mfma_f32_16x16x32_bf16 v[76:79], v[142:145], v[238:241], v[76:79]
	v_mfma_f32_16x16x32_bf16 v[128:131], v[138:141], v[226:229], v[128:131]
	v_mfma_f32_16x16x32_bf16 v[124:127], v[146:149], v[226:229], v[124:127]
	v_mfma_f32_16x16x32_bf16 v[112:115], v[138:141], v[230:233], v[112:115]
	v_mfma_f32_16x16x32_bf16 v[108:111], v[146:149], v[230:233], v[108:111]
	v_mfma_f32_16x16x32_bf16 v[96:99], v[138:141], v[242:245], v[96:99]
	v_mfma_f32_16x16x32_bf16 v[92:95], v[146:149], v[242:245], v[92:95]
	v_mfma_f32_16x16x32_bf16 v[80:83], v[138:141], v[246:249], v[80:83]
	v_mfma_f32_16x16x32_bf16 v[76:79], v[146:149], v[246:249], v[76:79]
	v_mfma_f32_16x16x32_bf16 v[120:123], v[150:153], v[218:221], v[120:123]
	v_mfma_f32_16x16x32_bf16 v[116:119], v[178:181], v[218:221], v[116:119]
	v_mfma_f32_16x16x32_bf16 v[104:107], v[150:153], v[222:225], v[104:107]
	v_mfma_f32_16x16x32_bf16 v[100:103], v[178:181], v[222:225], v[100:103]
	v_mfma_f32_16x16x32_bf16 v[88:91], v[150:153], v[234:237], v[88:91]
	v_mfma_f32_16x16x32_bf16 v[84:87], v[178:181], v[234:237], v[84:87]
	v_mfma_f32_16x16x32_bf16 v[72:75], v[150:153], v[238:241], v[72:75]
	v_mfma_f32_16x16x32_bf16 v[68:71], v[178:181], v[238:241], v[68:71]
	v_mfma_f32_16x16x32_bf16 v[120:123], v[174:177], v[226:229], v[120:123]
	v_mfma_f32_16x16x32_bf16 v[116:119], v[182:185], v[226:229], v[116:119]
	v_mfma_f32_16x16x32_bf16 v[104:107], v[174:177], v[230:233], v[104:107]
	v_mfma_f32_16x16x32_bf16 v[100:103], v[182:185], v[230:233], v[100:103]
	v_mfma_f32_16x16x32_bf16 v[88:91], v[174:177], v[242:245], v[88:91]
	v_mfma_f32_16x16x32_bf16 v[84:87], v[182:185], v[242:245], v[84:87]
	v_mfma_f32_16x16x32_bf16 v[72:75], v[174:177], v[246:249], v[72:75]
	v_mfma_f32_16x16x32_bf16 v[68:71], v[182:185], v[246:249], v[68:71]
	s_barrier
	s_add_i32 s24, s70, s77
	v_lshl_add_u64 v[250:251], v[154:155], 0, s[48:49]
	s_mov_b32 m0, s24
	ds_read_b128 v[218:221], v207 offset:49152
	ds_read_b128 v[222:225], v207 offset:51200
	ds_read_b128 v[226:229], v208 offset:49152
	ds_read_b128 v[230:233], v208 offset:51200
	ds_read_b128 v[234:237], v207 offset:53248
	ds_read_b128 v[238:241], v207 offset:55296
	ds_read_b128 v[242:245], v208 offset:53248
	ds_read_b128 v[246:249], v208 offset:55296
	global_load_lds_dwordx4 v[250:251], off
	v_lshl_add_u64 v[250:251], v[154:155], 0, s[50:51]
	s_add_i32 m0, s24, 0x2000
	s_add_i32 s24, s71, s77
	global_load_lds_dwordx4 v[250:251], off
	v_lshl_add_u64 v[250:251], v[154:155], 0, s[52:53]
	s_mov_b32 m0, s24
	v_lshl_add_u64 v[154:155], v[154:155], 0, s[54:55]
	global_load_lds_dwordx4 v[250:251], off
	s_add_i32 m0, s24, 0x2000
	s_nop 0
	global_load_lds_dwordx4 v[154:155], off
	s_waitcnt vmcnt(4)
	s_waitcnt lgkmcnt(0)
	s_barrier
	v_mfma_f32_16x16x32_bf16 v[64:67], v[134:137], v[218:221], v[64:67]
	v_mfma_f32_16x16x32_bf16 v[60:63], v[142:145], v[218:221], v[60:63]
	v_mfma_f32_16x16x32_bf16 v[48:51], v[134:137], v[222:225], v[48:51]
	v_mfma_f32_16x16x32_bf16 v[44:47], v[142:145], v[222:225], v[44:47]
	v_mfma_f32_16x16x32_bf16 v[32:35], v[134:137], v[234:237], v[32:35]
	v_mfma_f32_16x16x32_bf16 v[28:31], v[142:145], v[234:237], v[28:31]
	v_mfma_f32_16x16x32_bf16 v[16:19], v[134:137], v[238:241], v[16:19]
	v_mfma_f32_16x16x32_bf16 v[12:15], v[142:145], v[238:241], v[12:15]
	v_mfma_f32_16x16x32_bf16 v[64:67], v[138:141], v[226:229], v[64:67]
	v_mfma_f32_16x16x32_bf16 v[60:63], v[146:149], v[226:229], v[60:63]
	v_mfma_f32_16x16x32_bf16 v[48:51], v[138:141], v[230:233], v[48:51]
	v_mfma_f32_16x16x32_bf16 v[44:47], v[146:149], v[230:233], v[44:47]
	v_mfma_f32_16x16x32_bf16 v[32:35], v[138:141], v[242:245], v[32:35]
	v_mfma_f32_16x16x32_bf16 v[28:31], v[146:149], v[242:245], v[28:31]
	v_mfma_f32_16x16x32_bf16 v[16:19], v[138:141], v[246:249], v[16:19]
	v_mfma_f32_16x16x32_bf16 v[12:15], v[146:149], v[246:249], v[12:15]
	v_mfma_f32_16x16x32_bf16 v[56:59], v[150:153], v[218:221], v[56:59]
	v_mfma_f32_16x16x32_bf16 v[52:55], v[178:181], v[218:221], v[52:55]
	v_mfma_f32_16x16x32_bf16 v[40:43], v[150:153], v[222:225], v[40:43]
	v_mfma_f32_16x16x32_bf16 v[36:39], v[178:181], v[222:225], v[36:39]
	v_mfma_f32_16x16x32_bf16 v[24:27], v[150:153], v[234:237], v[24:27]
	v_mfma_f32_16x16x32_bf16 v[20:23], v[178:181], v[234:237], v[20:23]
	v_mfma_f32_16x16x32_bf16 v[8:11], v[150:153], v[238:241], v[8:11]
	v_mfma_f32_16x16x32_bf16 v[4:7], v[178:181], v[238:241], v[4:7]
	v_mfma_f32_16x16x32_bf16 v[56:59], v[174:177], v[226:229], v[56:59]
	v_mfma_f32_16x16x32_bf16 v[52:55], v[182:185], v[226:229], v[52:55]
	v_mfma_f32_16x16x32_bf16 v[40:43], v[174:177], v[230:233], v[40:43]
	v_mfma_f32_16x16x32_bf16 v[36:39], v[182:185], v[230:233], v[36:39]
	v_mfma_f32_16x16x32_bf16 v[24:27], v[174:177], v[242:245], v[24:27]
	v_mfma_f32_16x16x32_bf16 v[20:23], v[182:185], v[242:245], v[20:23]
	v_mfma_f32_16x16x32_bf16 v[8:11], v[174:177], v[246:249], v[8:11]
	v_mfma_f32_16x16x32_bf16 v[4:7], v[182:185], v[246:249], v[4:7]
	s_add_i32 s94, s94, 2
	s_add_u32 vcc_lo, vcc_lo, 0x100
	s_addc_u32 vcc_hi, vcc_hi, 0
	s_cmp_gt_u32 s94, 13
	s_barrier
.LBB0_384:
	ds_read_b128 v[134:137], v199
	ds_read_b128 v[138:141], v200
	ds_read_b128 v[142:145], v201
	ds_read_b128 v[146:149], v202
	ds_read_b128 v[150:153], v203
	ds_read_b128 v[174:177], v204
	ds_read_b128 v[178:181], v205
	ds_read_b128 v[182:185], v206
	s_add_u32 s24, s4, vcc_lo
	s_addc_u32 s25, s5, vcc_hi
	s_add_u32 s24, s24, 0x100
	s_addc_u32 s25, s25, 0
	s_add_u32 s82, s39, vcc_lo
	s_addc_u32 s83, s67, vcc_hi
	s_cmpk_eq_i32 vcc_lo, 0x700
	s_cselect_b32 s87, s29, s83
	s_cselect_b32 s86, s38, s82
	s_cselect_b32 s83, s34, s25
	s_cselect_b32 s82, s35, s24
	v_lshl_add_u64 v[154:155], v[132:133], 0, vcc
	v_lshl_add_u64 v[250:251], v[154:155], 0, s[48:49]
	s_add_i32 m0, s79, 0x8000
	s_mov_b64 s[24:25], 0x20080
	ds_read_b128 v[218:221], v207
	ds_read_b128 v[222:225], v207 offset:2048
	ds_read_b128 v[226:229], v208
	ds_read_b128 v[230:233], v208 offset:2048
	ds_read_b128 v[234:237], v207 offset:4096
	ds_read_b128 v[238:241], v207 offset:6144
	ds_read_b128 v[242:245], v208 offset:4096
	ds_read_b128 v[246:249], v208 offset:6144
	global_load_lds_dwordx4 v[250:251], off
	v_lshl_add_u64 v[250:251], v[154:155], 0, s[24:25]
	s_add_i32 m0, s79, 0xa000
	s_mov_b64 s[24:25], 0x60080
	global_load_lds_dwordx4 v[250:251], off
	v_lshl_add_u64 v[250:251], v[154:155], 0, s[50:51]
	s_add_i32 m0, s79, 0xc000
	v_lshl_add_u64 v[154:155], v[154:155], 0, s[24:25]
	global_load_lds_dwordx4 v[250:251], off
	s_add_i32 m0, s79, 0xe000
	s_nop 0
	global_load_lds_dwordx4 v[154:155], off
	s_waitcnt vmcnt(8)
	s_waitcnt lgkmcnt(0)
	s_barrier
	v_mfma_f32_16x16x32_bf16 v[128:131], v[134:137], v[218:221], v[128:131]
	v_mfma_f32_16x16x32_bf16 v[124:127], v[142:145], v[218:221], v[124:127]
	v_mfma_f32_16x16x32_bf16 v[112:115], v[134:137], v[222:225], v[112:115]
	v_mfma_f32_16x16x32_bf16 v[108:111], v[142:145], v[222:225], v[108:111]
	v_mfma_f32_16x16x32_bf16 v[96:99], v[134:137], v[234:237], v[96:99]
	v_mfma_f32_16x16x32_bf16 v[92:95], v[142:145], v[234:237], v[92:95]
	v_mfma_f32_16x16x32_bf16 v[80:83], v[134:137], v[238:241], v[80:83]
	v_mfma_f32_16x16x32_bf16 v[76:79], v[142:145], v[238:241], v[76:79]
	v_mfma_f32_16x16x32_bf16 v[128:131], v[138:141], v[226:229], v[128:131]
	v_mfma_f32_16x16x32_bf16 v[124:127], v[146:149], v[226:229], v[124:127]
	v_mfma_f32_16x16x32_bf16 v[112:115], v[138:141], v[230:233], v[112:115]
	v_mfma_f32_16x16x32_bf16 v[108:111], v[146:149], v[230:233], v[108:111]
	v_mfma_f32_16x16x32_bf16 v[96:99], v[138:141], v[242:245], v[96:99]
	v_mfma_f32_16x16x32_bf16 v[92:95], v[146:149], v[242:245], v[92:95]
	v_mfma_f32_16x16x32_bf16 v[80:83], v[138:141], v[246:249], v[80:83]
	v_mfma_f32_16x16x32_bf16 v[76:79], v[146:149], v[246:249], v[76:79]
	v_mfma_f32_16x16x32_bf16 v[120:123], v[150:153], v[218:221], v[120:123]
	v_mfma_f32_16x16x32_bf16 v[116:119], v[178:181], v[218:221], v[116:119]
	v_mfma_f32_16x16x32_bf16 v[104:107], v[150:153], v[222:225], v[104:107]
	v_mfma_f32_16x16x32_bf16 v[100:103], v[178:181], v[222:225], v[100:103]
	v_mfma_f32_16x16x32_bf16 v[88:91], v[150:153], v[234:237], v[88:91]
	v_mfma_f32_16x16x32_bf16 v[84:87], v[178:181], v[234:237], v[84:87]
	v_mfma_f32_16x16x32_bf16 v[72:75], v[150:153], v[238:241], v[72:75]
	v_mfma_f32_16x16x32_bf16 v[68:71], v[178:181], v[238:241], v[68:71]
	v_mfma_f32_16x16x32_bf16 v[120:123], v[174:177], v[226:229], v[120:123]
	v_mfma_f32_16x16x32_bf16 v[116:119], v[182:185], v[226:229], v[116:119]
	v_mfma_f32_16x16x32_bf16 v[104:107], v[174:177], v[230:233], v[104:107]
	v_mfma_f32_16x16x32_bf16 v[100:103], v[182:185], v[230:233], v[100:103]
	v_mfma_f32_16x16x32_bf16 v[88:91], v[174:177], v[242:245], v[88:91]
	v_mfma_f32_16x16x32_bf16 v[84:87], v[182:185], v[242:245], v[84:87]
	v_mfma_f32_16x16x32_bf16 v[72:75], v[174:177], v[246:249], v[72:75]
	v_mfma_f32_16x16x32_bf16 v[68:71], v[182:185], v[246:249], v[68:71]
	s_barrier
	s_add_i32 s24, s1, s77
	v_lshl_add_u64 v[154:155], s[86:87], 0, v[158:159]
	s_mov_b32 m0, s24
	ds_read_b128 v[218:221], v207 offset:16384
	ds_read_b128 v[222:225], v207 offset:18432
	ds_read_b128 v[226:229], v208 offset:16384
	ds_read_b128 v[230:233], v208 offset:18432
	ds_read_b128 v[234:237], v207 offset:20480
	ds_read_b128 v[238:241], v207 offset:22528
	ds_read_b128 v[242:245], v208 offset:20480
	ds_read_b128 v[246:249], v208 offset:22528
	global_load_lds_dwordx4 v[154:155], off
	v_lshl_add_u64 v[250:251], v[154:155], 0, s[14:15]
	s_add_i32 m0, s24, 0x2000
	s_add_i32 s24, s12, s77
	global_load_lds_dwordx4 v[250:251], off
	v_lshl_add_u64 v[250:251], v[154:155], 0, s[16:17]
	s_mov_b32 m0, s24
	s_nop 0
	global_load_lds_dwordx4 v[250:251], off
	v_lshl_add_u64 v[250:251], v[154:155], 0, s[18:19]
	s_add_i32 m0, s24, 0x2000
	s_nop 0
	global_load_lds_dwordx4 v[250:251], off
	s_waitcnt vmcnt(4)
	s_waitcnt lgkmcnt(0)
	s_barrier
	v_mfma_f32_16x16x32_bf16 v[64:67], v[134:137], v[218:221], v[64:67]
	v_mfma_f32_16x16x32_bf16 v[60:63], v[142:145], v[218:221], v[60:63]
	v_mfma_f32_16x16x32_bf16 v[48:51], v[134:137], v[222:225], v[48:51]
	v_mfma_f32_16x16x32_bf16 v[44:47], v[142:145], v[222:225], v[44:47]
	v_mfma_f32_16x16x32_bf16 v[32:35], v[134:137], v[234:237], v[32:35]
	v_mfma_f32_16x16x32_bf16 v[28:31], v[142:145], v[234:237], v[28:31]
	v_mfma_f32_16x16x32_bf16 v[16:19], v[134:137], v[238:241], v[16:19]
	v_mfma_f32_16x16x32_bf16 v[12:15], v[142:145], v[238:241], v[12:15]
	v_mfma_f32_16x16x32_bf16 v[64:67], v[138:141], v[226:229], v[64:67]
	v_mfma_f32_16x16x32_bf16 v[60:63], v[146:149], v[226:229], v[60:63]
	v_mfma_f32_16x16x32_bf16 v[48:51], v[138:141], v[230:233], v[48:51]
	v_mfma_f32_16x16x32_bf16 v[44:47], v[146:149], v[230:233], v[44:47]
	v_mfma_f32_16x16x32_bf16 v[32:35], v[138:141], v[242:245], v[32:35]
	v_mfma_f32_16x16x32_bf16 v[28:31], v[146:149], v[242:245], v[28:31]
	v_mfma_f32_16x16x32_bf16 v[16:19], v[138:141], v[246:249], v[16:19]
	v_mfma_f32_16x16x32_bf16 v[12:15], v[146:149], v[246:249], v[12:15]
	v_mfma_f32_16x16x32_bf16 v[56:59], v[150:153], v[218:221], v[56:59]
	v_mfma_f32_16x16x32_bf16 v[52:55], v[178:181], v[218:221], v[52:55]
	v_mfma_f32_16x16x32_bf16 v[40:43], v[150:153], v[222:225], v[40:43]
	v_mfma_f32_16x16x32_bf16 v[36:39], v[178:181], v[222:225], v[36:39]
	v_mfma_f32_16x16x32_bf16 v[24:27], v[150:153], v[234:237], v[24:27]
	v_mfma_f32_16x16x32_bf16 v[20:23], v[178:181], v[234:237], v[20:23]
	v_mfma_f32_16x16x32_bf16 v[8:11], v[150:153], v[238:241], v[8:11]
	v_mfma_f32_16x16x32_bf16 v[4:7], v[178:181], v[238:241], v[4:7]
	v_mfma_f32_16x16x32_bf16 v[56:59], v[174:177], v[226:229], v[56:59]
	v_mfma_f32_16x16x32_bf16 v[52:55], v[182:185], v[226:229], v[52:55]
	v_mfma_f32_16x16x32_bf16 v[40:43], v[174:177], v[230:233], v[40:43]
	v_mfma_f32_16x16x32_bf16 v[36:39], v[182:185], v[230:233], v[36:39]
	v_mfma_f32_16x16x32_bf16 v[24:27], v[174:177], v[242:245], v[24:27]
	v_mfma_f32_16x16x32_bf16 v[20:23], v[182:185], v[242:245], v[20:23]
	v_mfma_f32_16x16x32_bf16 v[8:11], v[174:177], v[246:249], v[8:11]
	v_mfma_f32_16x16x32_bf16 v[4:7], v[182:185], v[246:249], v[4:7]
	s_barrier
	ds_read_b128 v[134:137], v213
	ds_read_b128 v[138:141], v214
	ds_read_b128 v[142:145], v209
	ds_read_b128 v[146:149], v210
	ds_read_b128 v[150:153], v215
	ds_read_b128 v[174:177], v216
	ds_read_b128 v[178:181], v211
	ds_read_b128 v[182:185], v212
	s_mov_b32 m0, s79
	v_lshl_add_u64 v[250:251], s[82:83], 0, v[0:1]
	ds_read_b128 v[218:221], v207 offset:32768
	ds_read_b128 v[222:225], v207 offset:34816
	ds_read_b128 v[226:229], v208 offset:32768
	ds_read_b128 v[230:233], v208 offset:34816
	ds_read_b128 v[234:237], v207 offset:36864
	ds_read_b128 v[238:241], v207 offset:38912
	ds_read_b128 v[242:245], v208 offset:36864
	ds_read_b128 v[246:249], v208 offset:38912
	global_load_lds_dwordx4 v[250:251], off
	v_lshl_add_u64 v[252:253], v[250:251], 0, s[20:21]
	s_mov_b32 m0, s81
	s_nop 0
	global_load_lds_dwordx4 v[252:253], off
	v_lshl_add_u64 v[252:253], v[250:251], 0, s[14:15]
	s_mov_b32 m0, s97
	v_lshl_add_u64 v[250:251], v[250:251], 0, s[22:23]
	global_load_lds_dwordx4 v[252:253], off
	s_mov_b32 m0, s64
	s_nop 0
	global_load_lds_dwordx4 v[250:251], off
	s_waitcnt vmcnt(8)
	s_waitcnt lgkmcnt(0)
	s_barrier
	v_mfma_f32_16x16x32_bf16 v[128:131], v[134:137], v[218:221], v[128:131]
	v_mfma_f32_16x16x32_bf16 v[124:127], v[142:145], v[218:221], v[124:127]
	v_mfma_f32_16x16x32_bf16 v[112:115], v[134:137], v[222:225], v[112:115]
	v_mfma_f32_16x16x32_bf16 v[108:111], v[142:145], v[222:225], v[108:111]
	v_mfma_f32_16x16x32_bf16 v[96:99], v[134:137], v[234:237], v[96:99]
	v_mfma_f32_16x16x32_bf16 v[92:95], v[142:145], v[234:237], v[92:95]
	v_mfma_f32_16x16x32_bf16 v[80:83], v[134:137], v[238:241], v[80:83]
	v_mfma_f32_16x16x32_bf16 v[76:79], v[142:145], v[238:241], v[76:79]
	v_mfma_f32_16x16x32_bf16 v[128:131], v[138:141], v[226:229], v[128:131]
	v_mfma_f32_16x16x32_bf16 v[124:127], v[146:149], v[226:229], v[124:127]
	v_mfma_f32_16x16x32_bf16 v[112:115], v[138:141], v[230:233], v[112:115]
	v_mfma_f32_16x16x32_bf16 v[108:111], v[146:149], v[230:233], v[108:111]
	v_mfma_f32_16x16x32_bf16 v[96:99], v[138:141], v[242:245], v[96:99]
	v_mfma_f32_16x16x32_bf16 v[92:95], v[146:149], v[242:245], v[92:95]
	v_mfma_f32_16x16x32_bf16 v[80:83], v[138:141], v[246:249], v[80:83]
	v_mfma_f32_16x16x32_bf16 v[76:79], v[146:149], v[246:249], v[76:79]
	v_mfma_f32_16x16x32_bf16 v[120:123], v[150:153], v[218:221], v[120:123]
	v_mfma_f32_16x16x32_bf16 v[116:119], v[178:181], v[218:221], v[116:119]
	v_mfma_f32_16x16x32_bf16 v[104:107], v[150:153], v[222:225], v[104:107]
	v_mfma_f32_16x16x32_bf16 v[100:103], v[178:181], v[222:225], v[100:103]
	v_mfma_f32_16x16x32_bf16 v[88:91], v[150:153], v[234:237], v[88:91]
	v_mfma_f32_16x16x32_bf16 v[84:87], v[178:181], v[234:237], v[84:87]
	v_mfma_f32_16x16x32_bf16 v[72:75], v[150:153], v[238:241], v[72:75]
	v_mfma_f32_16x16x32_bf16 v[68:71], v[178:181], v[238:241], v[68:71]
	v_mfma_f32_16x16x32_bf16 v[120:123], v[174:177], v[226:229], v[120:123]
	v_mfma_f32_16x16x32_bf16 v[116:119], v[182:185], v[226:229], v[116:119]
	v_mfma_f32_16x16x32_bf16 v[104:107], v[174:177], v[230:233], v[104:107]
	v_mfma_f32_16x16x32_bf16 v[100:103], v[182:185], v[230:233], v[100:103]
	v_mfma_f32_16x16x32_bf16 v[88:91], v[174:177], v[242:245], v[88:91]
	v_mfma_f32_16x16x32_bf16 v[84:87], v[182:185], v[242:245], v[84:87]
	v_mfma_f32_16x16x32_bf16 v[72:75], v[174:177], v[246:249], v[72:75]
	v_mfma_f32_16x16x32_bf16 v[68:71], v[182:185], v[246:249], v[68:71]
	s_barrier
	s_add_i32 s24, s70, s77
	v_lshl_add_u64 v[250:251], v[154:155], 0, s[48:49]
	s_mov_b32 m0, s24
	ds_read_b128 v[218:221], v207 offset:49152
	ds_read_b128 v[222:225], v207 offset:51200
	ds_read_b128 v[226:229], v208 offset:49152
	ds_read_b128 v[230:233], v208 offset:51200
	ds_read_b128 v[234:237], v207 offset:53248
	ds_read_b128 v[238:241], v207 offset:55296
	ds_read_b128 v[242:245], v208 offset:53248
	ds_read_b128 v[246:249], v208 offset:55296
	global_load_lds_dwordx4 v[250:251], off
	v_lshl_add_u64 v[250:251], v[154:155], 0, s[50:51]
	s_add_i32 m0, s24, 0x2000
	s_add_i32 s24, s71, s77
	global_load_lds_dwordx4 v[250:251], off
	v_lshl_add_u64 v[250:251], v[154:155], 0, s[52:53]
	s_mov_b32 m0, s24
	v_lshl_add_u64 v[154:155], v[154:155], 0, s[54:55]
	global_load_lds_dwordx4 v[250:251], off
	s_add_i32 m0, s24, 0x2000
	s_nop 0
	global_load_lds_dwordx4 v[154:155], off
	s_waitcnt vmcnt(4)
	s_waitcnt lgkmcnt(0)
	s_barrier
	v_mfma_f32_16x16x32_bf16 v[64:67], v[134:137], v[218:221], v[64:67]
	v_mfma_f32_16x16x32_bf16 v[60:63], v[142:145], v[218:221], v[60:63]
	v_mfma_f32_16x16x32_bf16 v[48:51], v[134:137], v[222:225], v[48:51]
	v_mfma_f32_16x16x32_bf16 v[44:47], v[142:145], v[222:225], v[44:47]
	v_mfma_f32_16x16x32_bf16 v[32:35], v[134:137], v[234:237], v[32:35]
	v_mfma_f32_16x16x32_bf16 v[28:31], v[142:145], v[234:237], v[28:31]
	v_mfma_f32_16x16x32_bf16 v[16:19], v[134:137], v[238:241], v[16:19]
	v_mfma_f32_16x16x32_bf16 v[12:15], v[142:145], v[238:241], v[12:15]
	v_mfma_f32_16x16x32_bf16 v[64:67], v[138:141], v[226:229], v[64:67]
	v_mfma_f32_16x16x32_bf16 v[60:63], v[146:149], v[226:229], v[60:63]
	v_mfma_f32_16x16x32_bf16 v[48:51], v[138:141], v[230:233], v[48:51]
	v_mfma_f32_16x16x32_bf16 v[44:47], v[146:149], v[230:233], v[44:47]
	v_mfma_f32_16x16x32_bf16 v[32:35], v[138:141], v[242:245], v[32:35]
	v_mfma_f32_16x16x32_bf16 v[28:31], v[146:149], v[242:245], v[28:31]
	v_mfma_f32_16x16x32_bf16 v[16:19], v[138:141], v[246:249], v[16:19]
	v_mfma_f32_16x16x32_bf16 v[12:15], v[146:149], v[246:249], v[12:15]
	v_mfma_f32_16x16x32_bf16 v[56:59], v[150:153], v[218:221], v[56:59]
	v_mfma_f32_16x16x32_bf16 v[52:55], v[178:181], v[218:221], v[52:55]
	v_mfma_f32_16x16x32_bf16 v[40:43], v[150:153], v[222:225], v[40:43]
	v_mfma_f32_16x16x32_bf16 v[36:39], v[178:181], v[222:225], v[36:39]
	v_mfma_f32_16x16x32_bf16 v[24:27], v[150:153], v[234:237], v[24:27]
	v_mfma_f32_16x16x32_bf16 v[20:23], v[178:181], v[234:237], v[20:23]
	v_mfma_f32_16x16x32_bf16 v[8:11], v[150:153], v[238:241], v[8:11]
	v_mfma_f32_16x16x32_bf16 v[4:7], v[178:181], v[238:241], v[4:7]
	v_mfma_f32_16x16x32_bf16 v[56:59], v[174:177], v[226:229], v[56:59]
	v_mfma_f32_16x16x32_bf16 v[52:55], v[182:185], v[226:229], v[52:55]
	v_mfma_f32_16x16x32_bf16 v[40:43], v[174:177], v[230:233], v[40:43]
	v_mfma_f32_16x16x32_bf16 v[36:39], v[182:185], v[230:233], v[36:39]
	v_mfma_f32_16x16x32_bf16 v[24:27], v[174:177], v[242:245], v[24:27]
	v_mfma_f32_16x16x32_bf16 v[20:23], v[182:185], v[242:245], v[20:23]
	v_mfma_f32_16x16x32_bf16 v[8:11], v[174:177], v[246:249], v[8:11]
	v_mfma_f32_16x16x32_bf16 v[4:7], v[182:185], v[246:249], v[4:7]
	s_add_i32 s94, s94, 2
	s_add_u32 vcc_lo, vcc_lo, 0x100
	s_addc_u32 vcc_hi, vcc_hi, 0
	s_cmp_gt_u32 s94, 13
	s_barrier
	s_cbranch_scc0 .LBB0_384
	s_and_b64 vcc, exec, s[56:57]
	s_cbranch_vccz .LBB0_387
	s_barrier

.LBB0_779:
	v_add_u32_e32 v4, s73, v159
	v_add_u32_e32 v6, s73, v173
	ds_read_b128 v[136:139], v4
	ds_read_b128 v[140:143], v6
	v_add_u32_e32 v4, s77, v159
	s_add_u32 s26, s28, s64
	v_add_u32_e32 v6, s77, v173
	ds_read_b128 v[180:183], v4
	ds_read_b128 v[196:199], v6
	v_add_u32_e32 v4, s79, v159
	s_addc_u32 s27, s29, s65
	v_add_u32_e32 v6, s79, v173
	ds_read_b128 v[200:203], v4
	ds_read_b128 v[204:207], v6
	v_add_u32_e32 v4, s80, v159
	s_add_u32 s26, s26, 0x100
	v_add_u32_e32 v6, s80, v173
	ds_read_b128 v[208:211], v4
	ds_read_b128 v[212:215], v6
	s_addc_u32 s27, s27, 0
	s_add_u32 s34, s93, s64
	s_addc_u32 s35, s94, s65
	s_cmpk_eq_i32 s64, 0xb00
	s_cselect_b32 s35, s63, s35
	s_cselect_b32 s34, s62, s34
	s_cselect_b32 s27, s1, s27
	s_cselect_b32 s26, s0, s26
	v_lshl_add_u64 v[6:7], v[170:171], 0, s[64:65]
	v_lshl_add_u64 v[184:185], v[6:7], 0, s[24:25]
	s_add_i32 m0, s66, 0x8000
	s_mov_b64 s[38:39], 0x30080
	ds_read_b128 v[216:219], v176
	ds_read_b128 v[220:223], v176 offset:2048
	ds_read_b128 v[224:227], v177
	ds_read_b128 v[228:231], v177 offset:2048
	ds_read_b128 v[232:235], v176 offset:4096
	ds_read_b128 v[236:239], v176 offset:6144
	ds_read_b128 v[240:243], v177 offset:4096
	ds_read_b128 v[244:247], v177 offset:6144
	global_load_lds_dwordx4 v[184:185], off
	v_lshl_add_u64 v[184:185], v[6:7], 0, s[38:39]
	s_add_i32 m0, s66, 0xa000
	s_mov_b64 s[38:39], 0x90080
	global_load_lds_dwordx4 v[184:185], off
	v_lshl_add_u64 v[184:185], v[6:7], 0, s[50:51]
	s_add_i32 m0, s66, 0xc000
	v_lshl_add_u64 v[6:7], v[6:7], 0, s[38:39]
	global_load_lds_dwordx4 v[184:185], off
	s_add_i32 m0, s66, 0xe000
	s_nop 0
	global_load_lds_dwordx4 v[6:7], off
	s_waitcnt vmcnt(8)
	s_waitcnt lgkmcnt(0)
	s_barrier
	v_mfma_f32_16x16x32_bf16 v[132:135], v[136:139], v[216:219], v[132:135]
	v_mfma_f32_16x16x32_bf16 v[128:131], v[180:183], v[216:219], v[128:131]
	v_mfma_f32_16x16x32_bf16 v[116:119], v[136:139], v[220:223], v[116:119]
	v_mfma_f32_16x16x32_bf16 v[112:115], v[180:183], v[220:223], v[112:115]
	v_mfma_f32_16x16x32_bf16 v[100:103], v[136:139], v[232:235], v[100:103]
	v_mfma_f32_16x16x32_bf16 v[96:99], v[180:183], v[232:235], v[96:99]
	v_mfma_f32_16x16x32_bf16 v[84:87], v[136:139], v[236:239], v[84:87]
	v_mfma_f32_16x16x32_bf16 v[80:83], v[180:183], v[236:239], v[80:83]
	v_mfma_f32_16x16x32_bf16 v[132:135], v[140:143], v[224:227], v[132:135]
	v_mfma_f32_16x16x32_bf16 v[128:131], v[196:199], v[224:227], v[128:131]
	v_mfma_f32_16x16x32_bf16 v[116:119], v[140:143], v[228:231], v[116:119]
	v_mfma_f32_16x16x32_bf16 v[112:115], v[196:199], v[228:231], v[112:115]
	v_mfma_f32_16x16x32_bf16 v[100:103], v[140:143], v[240:243], v[100:103]
	v_mfma_f32_16x16x32_bf16 v[96:99], v[196:199], v[240:243], v[96:99]
	v_mfma_f32_16x16x32_bf16 v[84:87], v[140:143], v[244:247], v[84:87]
	v_mfma_f32_16x16x32_bf16 v[80:83], v[196:199], v[244:247], v[80:83]
	v_mfma_f32_16x16x32_bf16 v[124:127], v[200:203], v[216:219], v[124:127]
	v_mfma_f32_16x16x32_bf16 v[120:123], v[208:211], v[216:219], v[120:123]
	v_mfma_f32_16x16x32_bf16 v[108:111], v[200:203], v[220:223], v[108:111]
	v_mfma_f32_16x16x32_bf16 v[104:107], v[208:211], v[220:223], v[104:107]
	v_mfma_f32_16x16x32_bf16 v[92:95], v[200:203], v[232:235], v[92:95]
	v_mfma_f32_16x16x32_bf16 v[88:91], v[208:211], v[232:235], v[88:91]
	v_mfma_f32_16x16x32_bf16 v[76:79], v[200:203], v[236:239], v[76:79]
	v_mfma_f32_16x16x32_bf16 v[72:75], v[208:211], v[236:239], v[72:75]
	v_mfma_f32_16x16x32_bf16 v[124:127], v[204:207], v[224:227], v[124:127]
	v_mfma_f32_16x16x32_bf16 v[120:123], v[212:215], v[224:227], v[120:123]
	v_mfma_f32_16x16x32_bf16 v[108:111], v[204:207], v[228:231], v[108:111]
	v_mfma_f32_16x16x32_bf16 v[104:107], v[212:215], v[228:231], v[104:107]
	v_mfma_f32_16x16x32_bf16 v[92:95], v[204:207], v[240:243], v[92:95]
	v_mfma_f32_16x16x32_bf16 v[88:91], v[212:215], v[240:243], v[88:91]
	v_mfma_f32_16x16x32_bf16 v[76:79], v[204:207], v[244:247], v[76:79]
	v_mfma_f32_16x16x32_bf16 v[72:75], v[212:215], v[244:247], v[72:75]
	s_barrier
	v_lshl_add_u64 v[184:185], s[34:35], 0, v[146:147]
	s_add_i32 s34, s73, s3
	s_mov_b32 m0, s34
	ds_read_b128 v[216:219], v176 offset:16384
	ds_read_b128 v[220:223], v176 offset:18432
	ds_read_b128 v[224:227], v177 offset:16384
	ds_read_b128 v[228:231], v177 offset:18432
	ds_read_b128 v[232:235], v176 offset:20480
	ds_read_b128 v[236:239], v176 offset:22528
	ds_read_b128 v[240:243], v177 offset:20480
	ds_read_b128 v[244:247], v177 offset:22528
	global_load_lds_dwordx4 v[184:185], off
	v_lshl_add_u64 v[6:7], v[184:185], 0, s[12:13]
	s_add_i32 m0, s34, 0x2000
	s_add_i32 s34, s79, s3
	global_load_lds_dwordx4 v[6:7], off
	v_lshl_add_u64 v[6:7], v[184:185], 0, s[14:15]
	s_mov_b32 m0, s34
	s_nop 0
	global_load_lds_dwordx4 v[6:7], off
	v_lshl_add_u64 v[6:7], v[184:185], 0, s[16:17]
	s_add_i32 m0, s34, 0x2000
	s_nop 0
	global_load_lds_dwordx4 v[6:7], off
	s_waitcnt vmcnt(4)
	s_waitcnt lgkmcnt(0)
	s_barrier
	v_mfma_f32_16x16x32_bf16 v[68:71], v[136:139], v[216:219], v[68:71]
	v_mfma_f32_16x16x32_bf16 v[64:67], v[180:183], v[216:219], v[64:67]
	v_mfma_f32_16x16x32_bf16 v[52:55], v[136:139], v[220:223], v[52:55]
	v_mfma_f32_16x16x32_bf16 v[48:51], v[180:183], v[220:223], v[48:51]
	v_mfma_f32_16x16x32_bf16 v[36:39], v[136:139], v[232:235], v[36:39]
	v_mfma_f32_16x16x32_bf16 v[32:35], v[180:183], v[232:235], v[32:35]
	v_mfma_f32_16x16x32_bf16 v[20:23], v[136:139], v[236:239], v[20:23]
	v_mfma_f32_16x16x32_bf16 v[16:19], v[180:183], v[236:239], v[16:19]
	v_mfma_f32_16x16x32_bf16 v[68:71], v[140:143], v[224:227], v[68:71]
	v_mfma_f32_16x16x32_bf16 v[64:67], v[196:199], v[224:227], v[64:67]
	v_mfma_f32_16x16x32_bf16 v[52:55], v[140:143], v[228:231], v[52:55]
	v_mfma_f32_16x16x32_bf16 v[48:51], v[196:199], v[228:231], v[48:51]
	v_mfma_f32_16x16x32_bf16 v[36:39], v[140:143], v[240:243], v[36:39]
	v_mfma_f32_16x16x32_bf16 v[32:35], v[196:199], v[240:243], v[32:35]
	v_mfma_f32_16x16x32_bf16 v[20:23], v[140:143], v[244:247], v[20:23]
	v_mfma_f32_16x16x32_bf16 v[16:19], v[196:199], v[244:247], v[16:19]
	v_mfma_f32_16x16x32_bf16 v[60:63], v[200:203], v[216:219], v[60:63]
	v_mfma_f32_16x16x32_bf16 v[56:59], v[208:211], v[216:219], v[56:59]
	v_mfma_f32_16x16x32_bf16 v[44:47], v[200:203], v[220:223], v[44:47]
	v_mfma_f32_16x16x32_bf16 v[40:43], v[208:211], v[220:223], v[40:43]
	v_mfma_f32_16x16x32_bf16 v[28:31], v[200:203], v[232:235], v[28:31]
	v_mfma_f32_16x16x32_bf16 v[24:27], v[208:211], v[232:235], v[24:27]
	v_mfma_f32_16x16x32_bf16 v[12:15], v[200:203], v[236:239], v[12:15]
	v_mfma_f32_16x16x32_bf16 v[6:9], v[208:211], v[236:239], v[8:11]
	v_mfma_f32_16x16x32_bf16 v[60:63], v[204:207], v[224:227], v[60:63]
	v_mfma_f32_16x16x32_bf16 v[56:59], v[212:215], v[224:227], v[56:59]
	v_mfma_f32_16x16x32_bf16 v[44:47], v[204:207], v[228:231], v[44:47]
	v_mfma_f32_16x16x32_bf16 v[40:43], v[212:215], v[228:231], v[40:43]
	v_mfma_f32_16x16x32_bf16 v[28:31], v[204:207], v[240:243], v[28:31]
	v_mfma_f32_16x16x32_bf16 v[24:27], v[212:215], v[240:243], v[24:27]
	v_mfma_f32_16x16x32_bf16 v[12:15], v[204:207], v[244:247], v[12:15]
	v_mfma_f32_16x16x32_bf16 v[6:9], v[212:215], v[244:247], v[6:9]
	s_barrier
	v_add_u32_e32 v4, s83, v159
	v_add_u32_e32 v10, s83, v173
	ds_read_b128 v[136:139], v4
	ds_read_b128 v[140:143], v10
	v_add_u32_e32 v4, s81, v159
	v_add_u32_e32 v10, s81, v173
	ds_read_b128 v[180:183], v4
	ds_read_b128 v[196:199], v10
	v_add_u32_e32 v4, s84, v159
	v_add_u32_e32 v10, s84, v173
	ds_read_b128 v[200:203], v4
	ds_read_b128 v[204:207], v10
	v_add_u32_e32 v4, s82, v159
	v_add_u32_e32 v10, s82, v173
	ds_read_b128 v[208:211], v4
	ds_read_b128 v[212:215], v10
	s_mov_b32 m0, s66
	v_lshl_add_u64 v[10:11], s[26:27], 0, v[144:145]
	ds_read_b128 v[216:219], v176 offset:32768
	ds_read_b128 v[220:223], v176 offset:34816
	ds_read_b128 v[224:227], v177 offset:32768
	ds_read_b128 v[228:231], v177 offset:34816
	ds_read_b128 v[232:235], v176 offset:36864
	ds_read_b128 v[236:239], v176 offset:38912
	ds_read_b128 v[240:243], v177 offset:36864
	ds_read_b128 v[244:247], v177 offset:38912
	global_load_lds_dwordx4 v[10:11], off
	v_lshl_add_u64 v[248:249], v[10:11], 0, s[18:19]
	s_mov_b32 m0, s67
	s_nop 0
	global_load_lds_dwordx4 v[248:249], off
	v_lshl_add_u64 v[248:249], v[10:11], 0, s[12:13]
	s_mov_b32 m0, s68
	v_lshl_add_u64 v[10:11], v[10:11], 0, s[20:21]
	global_load_lds_dwordx4 v[248:249], off
	s_mov_b32 m0, s69
	s_nop 0
	global_load_lds_dwordx4 v[10:11], off
	s_waitcnt vmcnt(8)
	s_waitcnt lgkmcnt(0)
	s_barrier
	v_mfma_f32_16x16x32_bf16 v[132:135], v[136:139], v[216:219], v[132:135]
	v_mfma_f32_16x16x32_bf16 v[128:131], v[180:183], v[216:219], v[128:131]
	v_mfma_f32_16x16x32_bf16 v[116:119], v[136:139], v[220:223], v[116:119]
	v_mfma_f32_16x16x32_bf16 v[112:115], v[180:183], v[220:223], v[112:115]
	v_mfma_f32_16x16x32_bf16 v[100:103], v[136:139], v[232:235], v[100:103]
	v_mfma_f32_16x16x32_bf16 v[96:99], v[180:183], v[232:235], v[96:99]
	v_mfma_f32_16x16x32_bf16 v[84:87], v[136:139], v[236:239], v[84:87]
	v_mfma_f32_16x16x32_bf16 v[80:83], v[180:183], v[236:239], v[80:83]
	v_mfma_f32_16x16x32_bf16 v[132:135], v[140:143], v[224:227], v[132:135]
	v_mfma_f32_16x16x32_bf16 v[128:131], v[196:199], v[224:227], v[128:131]
	v_mfma_f32_16x16x32_bf16 v[116:119], v[140:143], v[228:231], v[116:119]
	v_mfma_f32_16x16x32_bf16 v[112:115], v[196:199], v[228:231], v[112:115]
	v_mfma_f32_16x16x32_bf16 v[100:103], v[140:143], v[240:243], v[100:103]
	v_mfma_f32_16x16x32_bf16 v[96:99], v[196:199], v[240:243], v[96:99]
	v_mfma_f32_16x16x32_bf16 v[84:87], v[140:143], v[244:247], v[84:87]
	v_mfma_f32_16x16x32_bf16 v[80:83], v[196:199], v[244:247], v[80:83]
	v_mfma_f32_16x16x32_bf16 v[124:127], v[200:203], v[216:219], v[124:127]
	v_mfma_f32_16x16x32_bf16 v[120:123], v[208:211], v[216:219], v[120:123]
	v_mfma_f32_16x16x32_bf16 v[108:111], v[200:203], v[220:223], v[108:111]
	v_mfma_f32_16x16x32_bf16 v[104:107], v[208:211], v[220:223], v[104:107]
	v_mfma_f32_16x16x32_bf16 v[92:95], v[200:203], v[232:235], v[92:95]
	v_mfma_f32_16x16x32_bf16 v[88:91], v[208:211], v[232:235], v[88:91]
	v_mfma_f32_16x16x32_bf16 v[76:79], v[200:203], v[236:239], v[76:79]
	v_mfma_f32_16x16x32_bf16 v[72:75], v[208:211], v[236:239], v[72:75]
	v_mfma_f32_16x16x32_bf16 v[124:127], v[204:207], v[224:227], v[124:127]
	v_mfma_f32_16x16x32_bf16 v[120:123], v[212:215], v[224:227], v[120:123]
	v_mfma_f32_16x16x32_bf16 v[108:111], v[204:207], v[228:231], v[108:111]
	v_mfma_f32_16x16x32_bf16 v[104:107], v[212:215], v[228:231], v[104:107]
	v_mfma_f32_16x16x32_bf16 v[92:95], v[204:207], v[240:243], v[92:95]
	v_mfma_f32_16x16x32_bf16 v[88:91], v[212:215], v[240:243], v[88:91]
	v_mfma_f32_16x16x32_bf16 v[76:79], v[204:207], v[244:247], v[76:79]
	v_mfma_f32_16x16x32_bf16 v[72:75], v[212:215], v[244:247], v[72:75]
	s_barrier
	s_add_i32 s26, s83, s3
	v_lshl_add_u64 v[10:11], v[184:185], 0, s[24:25]
	s_mov_b32 m0, s26
	ds_read_b128 v[216:219], v176 offset:49152
	ds_read_b128 v[220:223], v176 offset:51200
	ds_read_b128 v[224:227], v177 offset:49152
	ds_read_b128 v[228:231], v177 offset:51200
	ds_read_b128 v[232:235], v176 offset:53248
	ds_read_b128 v[236:239], v176 offset:55296
	ds_read_b128 v[240:243], v177 offset:53248
	ds_read_b128 v[244:247], v177 offset:55296
	global_load_lds_dwordx4 v[10:11], off
	v_lshl_add_u64 v[10:11], v[184:185], 0, s[50:51]
	s_add_i32 m0, s26, 0x2000
	s_add_i32 s26, s84, s3
	global_load_lds_dwordx4 v[10:11], off
	v_lshl_add_u64 v[10:11], v[184:185], 0, s[52:53]
	s_mov_b32 m0, s26
	s_nop 0
	global_load_lds_dwordx4 v[10:11], off
	v_lshl_add_u64 v[10:11], v[184:185], 0, s[54:55]
	s_add_i32 m0, s26, 0x2000
	s_nop 0
	global_load_lds_dwordx4 v[10:11], off
	s_waitcnt vmcnt(4)
	s_waitcnt lgkmcnt(0)
	s_barrier
	v_mfma_f32_16x16x32_bf16 v[68:71], v[136:139], v[216:219], v[68:71]
	v_mfma_f32_16x16x32_bf16 v[64:67], v[180:183], v[216:219], v[64:67]
	v_mfma_f32_16x16x32_bf16 v[52:55], v[136:139], v[220:223], v[52:55]
	v_mfma_f32_16x16x32_bf16 v[48:51], v[180:183], v[220:223], v[48:51]
	v_mfma_f32_16x16x32_bf16 v[36:39], v[136:139], v[232:235], v[36:39]
	v_mfma_f32_16x16x32_bf16 v[32:35], v[180:183], v[232:235], v[32:35]
	v_mfma_f32_16x16x32_bf16 v[20:23], v[136:139], v[236:239], v[20:23]
	v_mfma_f32_16x16x32_bf16 v[16:19], v[180:183], v[236:239], v[16:19]
	v_mfma_f32_16x16x32_bf16 v[68:71], v[140:143], v[224:227], v[68:71]
	v_mfma_f32_16x16x32_bf16 v[64:67], v[196:199], v[224:227], v[64:67]
	v_mfma_f32_16x16x32_bf16 v[52:55], v[140:143], v[228:231], v[52:55]
	v_mfma_f32_16x16x32_bf16 v[48:51], v[196:199], v[228:231], v[48:51]
	v_mfma_f32_16x16x32_bf16 v[36:39], v[140:143], v[240:243], v[36:39]
	v_mfma_f32_16x16x32_bf16 v[32:35], v[196:199], v[240:243], v[32:35]
	v_mfma_f32_16x16x32_bf16 v[20:23], v[140:143], v[244:247], v[20:23]
	v_mfma_f32_16x16x32_bf16 v[16:19], v[196:199], v[244:247], v[16:19]
	v_mfma_f32_16x16x32_bf16 v[60:63], v[200:203], v[216:219], v[60:63]
	v_mfma_f32_16x16x32_bf16 v[56:59], v[208:211], v[216:219], v[56:59]
	v_mfma_f32_16x16x32_bf16 v[44:47], v[200:203], v[220:223], v[44:47]
	v_mfma_f32_16x16x32_bf16 v[40:43], v[208:211], v[220:223], v[40:43]
	v_mfma_f32_16x16x32_bf16 v[28:31], v[200:203], v[232:235], v[28:31]
	v_mfma_f32_16x16x32_bf16 v[24:27], v[208:211], v[232:235], v[24:27]
	v_mfma_f32_16x16x32_bf16 v[10:13], v[200:203], v[236:239], v[12:15]
	v_mfma_f32_16x16x32_bf16 v[6:9], v[208:211], v[236:239], v[6:9]
	v_mfma_f32_16x16x32_bf16 v[60:63], v[204:207], v[224:227], v[60:63]
	v_mfma_f32_16x16x32_bf16 v[56:59], v[212:215], v[224:227], v[56:59]
	v_mfma_f32_16x16x32_bf16 v[44:47], v[204:207], v[228:231], v[44:47]
	v_mfma_f32_16x16x32_bf16 v[40:43], v[212:215], v[228:231], v[40:43]
	v_mfma_f32_16x16x32_bf16 v[28:31], v[204:207], v[240:243], v[28:31]
	v_mfma_f32_16x16x32_bf16 v[24:27], v[212:215], v[240:243], v[24:27]
	v_mfma_f32_16x16x32_bf16 v[12:15], v[204:207], v[244:247], v[10:13]
	v_mfma_f32_16x16x32_bf16 v[8:11], v[212:215], v[244:247], v[6:9]
	s_add_i32 s95, s95, 2
	s_add_u32 s64, s64, 0x100
	s_addc_u32 s65, s65, 0
	s_cmp_gt_u32 s95, 21
	s_barrier
	s_cbranch_scc1 .LBB0_782

.LBB0_973:
	v_add_u32_e32 v133, s72, v163
	v_add_u32_e32 v140, s72, v164
	ds_read_b128 v[136:139], v133
	ds_read_b128 v[148:151], v140
	v_add_u32_e32 v133, s73, v163
	s_add_u32 s70, s28, s26
	v_add_u32_e32 v140, s73, v164
	s_waitcnt lgkmcnt(0)
	ds_read_b128 v[152:155], v133
	ds_read_b128 v[174:177], v140
	v_add_u32_e32 v133, s77, v163
	s_addc_u32 s71, s29, s27
	v_add_u32_e32 v140, s77, v164
	ds_read_b128 v[178:181], v133
	ds_read_b128 v[182:185], v140
	v_add_u32_e32 v133, s79, v163
	s_add_u32 s70, s70, 0x100
	v_add_u32_e32 v140, s79, v164
	ds_read_b128 v[196:199], v133
	ds_read_b128 v[200:203], v140
	s_addc_u32 s71, s71, 0
	s_add_u32 s86, s65, s26
	s_addc_u32 s87, s85, s27
	s_cmpk_eq_i32 s26, 0x700
	s_cselect_b32 s87, s61, s87
	s_cselect_b32 s86, s88, s86
	s_cselect_b32 s71, s54, s71
	s_cselect_b32 s70, s63, s70
	v_lshl_add_u64 v[140:141], v[134:135], 0, s[26:27]
	v_lshl_add_u64 v[160:161], v[140:141], 0, s[36:37]
	s_add_i32 m0, s5, 0x8000
	s_mov_b64 s[90:91], 0x20080
	ds_read_b128 v[204:207], v166
	ds_read_b128 v[208:211], v166 offset:2048
	ds_read_b128 v[212:215], v167
	ds_read_b128 v[216:219], v167 offset:2048
	ds_read_b128 v[220:223], v166 offset:4096
	ds_read_b128 v[224:227], v166 offset:6144
	ds_read_b128 v[228:231], v167 offset:4096
	ds_read_b128 v[232:235], v167 offset:6144
	global_load_lds_dwordx4 v[160:161], off
	v_lshl_add_u64 v[160:161], v[140:141], 0, s[90:91]
	s_add_i32 m0, s5, 0xa000
	s_mov_b64 s[90:91], 0x60080
	global_load_lds_dwordx4 v[160:161], off
	v_lshl_add_u64 v[160:161], v[140:141], 0, s[44:45]
	s_add_i32 m0, s5, 0xc000
	v_lshl_add_u64 v[140:141], v[140:141], 0, s[90:91]
	global_load_lds_dwordx4 v[160:161], off
	s_add_i32 m0, s5, 0xe000
	s_nop 0
	global_load_lds_dwordx4 v[140:141], off
	s_waitcnt vmcnt(8)
	s_waitcnt lgkmcnt(0)
	s_barrier
	v_mfma_f32_16x16x32_bf16 v[8:11], v[136:139], v[204:207], v[8:11]
	v_mfma_f32_16x16x32_bf16 v[4:7], v[152:155], v[204:207], v[4:7]
	v_mfma_f32_16x16x32_bf16 v[12:15], v[136:139], v[208:211], v[12:15]
	v_mfma_f32_16x16x32_bf16 v[16:19], v[152:155], v[208:211], v[16:19]
	v_mfma_f32_16x16x32_bf16 v[44:47], v[136:139], v[220:223], v[44:47]
	v_mfma_f32_16x16x32_bf16 v[36:39], v[152:155], v[220:223], v[36:39]
	v_mfma_f32_16x16x32_bf16 v[20:23], v[136:139], v[224:227], v[20:23]
	v_mfma_f32_16x16x32_bf16 v[24:27], v[152:155], v[224:227], v[24:27]
	v_mfma_f32_16x16x32_bf16 v[8:11], v[148:151], v[212:215], v[8:11]
	v_mfma_f32_16x16x32_bf16 v[4:7], v[174:177], v[212:215], v[4:7]
	v_mfma_f32_16x16x32_bf16 v[12:15], v[148:151], v[216:219], v[12:15]
	v_mfma_f32_16x16x32_bf16 v[16:19], v[174:177], v[216:219], v[16:19]
	v_mfma_f32_16x16x32_bf16 v[44:47], v[148:151], v[228:231], v[44:47]
	v_mfma_f32_16x16x32_bf16 v[36:39], v[174:177], v[228:231], v[36:39]
	v_mfma_f32_16x16x32_bf16 v[20:23], v[148:151], v[232:235], v[20:23]
	v_mfma_f32_16x16x32_bf16 v[24:27], v[174:177], v[232:235], v[24:27]
	v_mfma_f32_16x16x32_bf16 v[32:35], v[178:181], v[204:207], v[32:35]
	v_mfma_f32_16x16x32_bf16 v[28:31], v[196:199], v[204:207], v[28:31]
	v_mfma_f32_16x16x32_bf16 v[40:43], v[178:181], v[208:211], v[40:43]
	v_mfma_f32_16x16x32_bf16 v[52:55], v[196:199], v[208:211], v[52:55]
	v_mfma_f32_16x16x32_bf16 v[48:51], v[178:181], v[220:223], v[48:51]
	v_mfma_f32_16x16x32_bf16 v[60:63], v[196:199], v[220:223], v[60:63]
	v_mfma_f32_16x16x32_bf16 v[56:59], v[178:181], v[224:227], v[56:59]
	v_mfma_f32_16x16x32_bf16 v[64:67], v[196:199], v[224:227], v[64:67]
	v_mfma_f32_16x16x32_bf16 v[32:35], v[182:185], v[212:215], v[32:35]
	v_mfma_f32_16x16x32_bf16 v[28:31], v[200:203], v[212:215], v[28:31]
	v_mfma_f32_16x16x32_bf16 v[40:43], v[182:185], v[216:219], v[40:43]
	v_mfma_f32_16x16x32_bf16 v[52:55], v[200:203], v[216:219], v[52:55]
	v_mfma_f32_16x16x32_bf16 v[48:51], v[182:185], v[228:231], v[48:51]
	v_mfma_f32_16x16x32_bf16 v[60:63], v[200:203], v[228:231], v[60:63]
	v_mfma_f32_16x16x32_bf16 v[56:59], v[182:185], v[232:235], v[56:59]
	v_mfma_f32_16x16x32_bf16 v[64:67], v[200:203], v[232:235], v[64:67]
	s_barrier
	v_lshl_add_u64 v[140:141], s[86:87], 0, v[158:159]
	s_add_i32 s86, s72, s34
	s_mov_b32 m0, s86
	ds_read_b128 v[204:207], v166 offset:16384
	ds_read_b128 v[208:211], v166 offset:18432
	ds_read_b128 v[212:215], v167 offset:16384
	ds_read_b128 v[216:219], v167 offset:18432
	ds_read_b128 v[220:223], v166 offset:20480
	ds_read_b128 v[224:227], v166 offset:22528
	ds_read_b128 v[228:231], v167 offset:20480
	ds_read_b128 v[232:235], v167 offset:22528
	global_load_lds_dwordx4 v[140:141], off
	v_lshl_add_u64 v[160:161], v[140:141], 0, s[18:19]
	s_add_i32 m0, s86, 0x2000
	s_mov_b64 s[86:87], 0x10000
	global_load_lds_dwordx4 v[160:161], off
	v_lshl_add_u64 v[160:161], v[140:141], 0, s[86:87]
	s_add_i32 s86, s77, s34
	s_mov_b32 m0, s86
	s_nop 0
	global_load_lds_dwordx4 v[160:161], off
	v_lshl_add_u64 v[160:161], v[140:141], 0, s[20:21]
	s_add_i32 m0, s86, 0x2000
	s_nop 0
	global_load_lds_dwordx4 v[160:161], off
	s_waitcnt vmcnt(4)
	s_waitcnt lgkmcnt(0)
	s_barrier
	v_mfma_f32_16x16x32_bf16 v[68:71], v[136:139], v[204:207], v[68:71]
	v_mfma_f32_16x16x32_bf16 v[72:75], v[152:155], v[204:207], v[72:75]
	v_mfma_f32_16x16x32_bf16 v[92:95], v[136:139], v[208:211], v[92:95]
	v_mfma_f32_16x16x32_bf16 v[84:87], v[152:155], v[208:211], v[84:87]
	v_mfma_f32_16x16x32_bf16 v[76:79], v[136:139], v[220:223], v[76:79]
	v_mfma_f32_16x16x32_bf16 v[80:83], v[152:155], v[220:223], v[80:83]
	v_mfma_f32_16x16x32_bf16 v[116:119], v[136:139], v[224:227], v[116:119]
	v_mfma_f32_16x16x32_bf16 v[108:111], v[152:155], v[224:227], v[108:111]
	v_mfma_f32_16x16x32_bf16 v[68:71], v[148:151], v[212:215], v[68:71]
	v_mfma_f32_16x16x32_bf16 v[72:75], v[174:177], v[212:215], v[72:75]
	v_mfma_f32_16x16x32_bf16 v[92:95], v[148:151], v[216:219], v[92:95]
	v_mfma_f32_16x16x32_bf16 v[84:87], v[174:177], v[216:219], v[84:87]
	v_mfma_f32_16x16x32_bf16 v[76:79], v[148:151], v[228:231], v[76:79]
	v_mfma_f32_16x16x32_bf16 v[80:83], v[174:177], v[228:231], v[80:83]
	v_mfma_f32_16x16x32_bf16 v[116:119], v[148:151], v[232:235], v[116:119]
	v_mfma_f32_16x16x32_bf16 v[108:111], v[174:177], v[232:235], v[108:111]
	v_mfma_f32_16x16x32_bf16 v[88:91], v[178:181], v[204:207], v[88:91]
	v_mfma_f32_16x16x32_bf16 v[100:103], v[196:199], v[204:207], v[100:103]
	v_mfma_f32_16x16x32_bf16 v[96:99], v[178:181], v[208:211], v[96:99]
	v_mfma_f32_16x16x32_bf16 v[104:107], v[196:199], v[208:211], v[104:107]
	v_mfma_f32_16x16x32_bf16 v[112:115], v[178:181], v[220:223], v[112:115]
	v_mfma_f32_16x16x32_bf16 v[124:127], v[196:199], v[220:223], v[124:127]
	v_mfma_f32_16x16x32_bf16 v[120:123], v[178:181], v[224:227], v[120:123]
	v_mfma_f32_16x16x32_bf16 v[128:131], v[196:199], v[224:227], v[128:131]
	v_mfma_f32_16x16x32_bf16 v[88:91], v[182:185], v[212:215], v[88:91]
	v_mfma_f32_16x16x32_bf16 v[100:103], v[200:203], v[212:215], v[100:103]
	v_mfma_f32_16x16x32_bf16 v[96:99], v[182:185], v[216:219], v[96:99]
	v_mfma_f32_16x16x32_bf16 v[104:107], v[200:203], v[216:219], v[104:107]
	v_mfma_f32_16x16x32_bf16 v[112:115], v[182:185], v[228:231], v[112:115]
	v_mfma_f32_16x16x32_bf16 v[124:127], v[200:203], v[228:231], v[124:127]
	v_mfma_f32_16x16x32_bf16 v[120:123], v[182:185], v[232:235], v[120:123]
	v_mfma_f32_16x16x32_bf16 v[128:131], v[200:203], v[232:235], v[128:131]
	s_barrier
	v_add_u32_e32 v133, s82, v163
	v_add_u32_e32 v148, s82, v164
	ds_read_b128 v[136:139], v133
	ds_read_b128 v[148:151], v148
	v_add_u32_e32 v133, s80, v163
	v_add_u32_e32 v160, s80, v164
	ds_read_b128 v[152:155], v133
	ds_read_b128 v[174:177], v160
	v_add_u32_e32 v133, s83, v163
	v_add_u32_e32 v160, s83, v164
	ds_read_b128 v[178:181], v133
	ds_read_b128 v[182:185], v160
	v_add_u32_e32 v133, s81, v163
	v_add_u32_e32 v160, s81, v164
	ds_read_b128 v[196:199], v133
	ds_read_b128 v[200:203], v160
	s_mov_b32 m0, s5
	v_lshl_add_u64 v[160:161], s[70:71], 0, v[0:1]
	s_mov_b64 s[70:71], 0x20000
	ds_read_b128 v[204:207], v166 offset:32768
	ds_read_b128 v[208:211], v166 offset:34816
	ds_read_b128 v[212:215], v167 offset:32768
	ds_read_b128 v[216:219], v167 offset:34816
	ds_read_b128 v[220:223], v166 offset:36864
	ds_read_b128 v[224:227], v166 offset:38912
	ds_read_b128 v[228:231], v167 offset:36864
	ds_read_b128 v[232:235], v167 offset:38912
	global_load_lds_dwordx4 v[160:161], off
	v_lshl_add_u64 v[170:171], v[160:161], 0, s[70:71]
	s_mov_b32 m0, s17
	s_nop 0
	global_load_lds_dwordx4 v[170:171], off
	v_lshl_add_u64 v[170:171], v[160:161], 0, s[18:19]
	s_mov_b32 m0, s35
	v_lshl_add_u64 v[160:161], v[160:161], 0, s[22:23]
	global_load_lds_dwordx4 v[170:171], off
	s_mov_b32 m0, s38
	s_nop 0
	global_load_lds_dwordx4 v[160:161], off
	s_waitcnt vmcnt(8)
	s_waitcnt lgkmcnt(0)
	s_barrier
	v_mfma_f32_16x16x32_bf16 v[8:11], v[136:139], v[204:207], v[8:11]
	v_mfma_f32_16x16x32_bf16 v[4:7], v[152:155], v[204:207], v[4:7]
	v_mfma_f32_16x16x32_bf16 v[12:15], v[136:139], v[208:211], v[12:15]
	v_mfma_f32_16x16x32_bf16 v[16:19], v[152:155], v[208:211], v[16:19]
	v_mfma_f32_16x16x32_bf16 v[44:47], v[136:139], v[220:223], v[44:47]
	v_mfma_f32_16x16x32_bf16 v[36:39], v[152:155], v[220:223], v[36:39]
	v_mfma_f32_16x16x32_bf16 v[20:23], v[136:139], v[224:227], v[20:23]
	v_mfma_f32_16x16x32_bf16 v[24:27], v[152:155], v[224:227], v[24:27]
	v_mfma_f32_16x16x32_bf16 v[8:11], v[148:151], v[212:215], v[8:11]
	v_mfma_f32_16x16x32_bf16 v[4:7], v[174:177], v[212:215], v[4:7]
	v_mfma_f32_16x16x32_bf16 v[12:15], v[148:151], v[216:219], v[12:15]
	v_mfma_f32_16x16x32_bf16 v[16:19], v[174:177], v[216:219], v[16:19]
	v_mfma_f32_16x16x32_bf16 v[44:47], v[148:151], v[228:231], v[44:47]
	v_mfma_f32_16x16x32_bf16 v[36:39], v[174:177], v[228:231], v[36:39]
	v_mfma_f32_16x16x32_bf16 v[20:23], v[148:151], v[232:235], v[20:23]
	v_mfma_f32_16x16x32_bf16 v[24:27], v[174:177], v[232:235], v[24:27]
	v_mfma_f32_16x16x32_bf16 v[32:35], v[178:181], v[204:207], v[32:35]
	v_mfma_f32_16x16x32_bf16 v[28:31], v[196:199], v[204:207], v[28:31]
	v_mfma_f32_16x16x32_bf16 v[40:43], v[178:181], v[208:211], v[40:43]
	v_mfma_f32_16x16x32_bf16 v[52:55], v[196:199], v[208:211], v[52:55]
	v_mfma_f32_16x16x32_bf16 v[48:51], v[178:181], v[220:223], v[48:51]
	v_mfma_f32_16x16x32_bf16 v[60:63], v[196:199], v[220:223], v[60:63]
	v_mfma_f32_16x16x32_bf16 v[56:59], v[178:181], v[224:227], v[56:59]
	v_mfma_f32_16x16x32_bf16 v[64:67], v[196:199], v[224:227], v[64:67]
	v_mfma_f32_16x16x32_bf16 v[32:35], v[182:185], v[212:215], v[32:35]
	v_mfma_f32_16x16x32_bf16 v[28:31], v[200:203], v[212:215], v[28:31]
	v_mfma_f32_16x16x32_bf16 v[40:43], v[182:185], v[216:219], v[40:43]
	v_mfma_f32_16x16x32_bf16 v[52:55], v[200:203], v[216:219], v[52:55]
	v_mfma_f32_16x16x32_bf16 v[48:51], v[182:185], v[228:231], v[48:51]
	v_mfma_f32_16x16x32_bf16 v[60:63], v[200:203], v[228:231], v[60:63]
	v_mfma_f32_16x16x32_bf16 v[56:59], v[182:185], v[232:235], v[56:59]
	v_mfma_f32_16x16x32_bf16 v[64:67], v[200:203], v[232:235], v[64:67]
	s_barrier
	s_add_i32 s70, s82, s34
	v_lshl_add_u64 v[160:161], v[140:141], 0, s[36:37]
	s_mov_b32 m0, s70
	ds_read_b128 v[204:207], v166 offset:49152
	ds_read_b128 v[208:211], v166 offset:51200
	ds_read_b128 v[212:215], v167 offset:49152
	ds_read_b128 v[216:219], v167 offset:51200
	ds_read_b128 v[220:223], v166 offset:53248
	ds_read_b128 v[224:227], v166 offset:55296
	ds_read_b128 v[228:231], v167 offset:53248
	ds_read_b128 v[232:235], v167 offset:55296
	global_load_lds_dwordx4 v[160:161], off
	v_lshl_add_u64 v[160:161], v[140:141], 0, s[44:45]
	s_add_i32 m0, s70, 0x2000
	s_add_i32 s70, s83, s34
	global_load_lds_dwordx4 v[160:161], off
	v_lshl_add_u64 v[160:161], v[140:141], 0, s[46:47]
	s_mov_b32 m0, s70
	v_lshl_add_u64 v[140:141], v[140:141], 0, s[50:51]
	global_load_lds_dwordx4 v[160:161], off
	s_add_i32 m0, s70, 0x2000
	s_nop 0
	global_load_lds_dwordx4 v[140:141], off
	s_waitcnt vmcnt(4)
	s_waitcnt lgkmcnt(0)
	s_barrier
	v_mfma_f32_16x16x32_bf16 v[68:71], v[136:139], v[204:207], v[68:71]
	v_mfma_f32_16x16x32_bf16 v[72:75], v[152:155], v[204:207], v[72:75]
	v_mfma_f32_16x16x32_bf16 v[92:95], v[136:139], v[208:211], v[92:95]
	v_mfma_f32_16x16x32_bf16 v[84:87], v[152:155], v[208:211], v[84:87]
	v_mfma_f32_16x16x32_bf16 v[76:79], v[136:139], v[220:223], v[76:79]
	v_mfma_f32_16x16x32_bf16 v[80:83], v[152:155], v[220:223], v[80:83]
	v_mfma_f32_16x16x32_bf16 v[116:119], v[136:139], v[224:227], v[116:119]
	v_mfma_f32_16x16x32_bf16 v[108:111], v[152:155], v[224:227], v[108:111]
	v_mfma_f32_16x16x32_bf16 v[68:71], v[148:151], v[212:215], v[68:71]
	v_mfma_f32_16x16x32_bf16 v[72:75], v[174:177], v[212:215], v[72:75]
	v_mfma_f32_16x16x32_bf16 v[92:95], v[148:151], v[216:219], v[92:95]
	v_mfma_f32_16x16x32_bf16 v[84:87], v[174:177], v[216:219], v[84:87]
	v_mfma_f32_16x16x32_bf16 v[76:79], v[148:151], v[228:231], v[76:79]
	v_mfma_f32_16x16x32_bf16 v[80:83], v[174:177], v[228:231], v[80:83]
	v_mfma_f32_16x16x32_bf16 v[116:119], v[148:151], v[232:235], v[116:119]
	v_mfma_f32_16x16x32_bf16 v[108:111], v[174:177], v[232:235], v[108:111]
	v_mfma_f32_16x16x32_bf16 v[88:91], v[178:181], v[204:207], v[88:91]
	v_mfma_f32_16x16x32_bf16 v[100:103], v[196:199], v[204:207], v[100:103]
	v_mfma_f32_16x16x32_bf16 v[96:99], v[178:181], v[208:211], v[96:99]
	v_mfma_f32_16x16x32_bf16 v[104:107], v[196:199], v[208:211], v[104:107]
	v_mfma_f32_16x16x32_bf16 v[112:115], v[178:181], v[220:223], v[112:115]
	v_mfma_f32_16x16x32_bf16 v[124:127], v[196:199], v[220:223], v[124:127]
	v_mfma_f32_16x16x32_bf16 v[120:123], v[178:181], v[224:227], v[120:123]
	v_mfma_f32_16x16x32_bf16 v[128:131], v[196:199], v[224:227], v[128:131]
	v_mfma_f32_16x16x32_bf16 v[88:91], v[182:185], v[212:215], v[88:91]
	v_mfma_f32_16x16x32_bf16 v[100:103], v[200:203], v[212:215], v[100:103]
	v_mfma_f32_16x16x32_bf16 v[96:99], v[182:185], v[216:219], v[96:99]
	v_mfma_f32_16x16x32_bf16 v[104:107], v[200:203], v[216:219], v[104:107]
	v_mfma_f32_16x16x32_bf16 v[112:115], v[182:185], v[228:231], v[112:115]
	v_mfma_f32_16x16x32_bf16 v[124:127], v[200:203], v[228:231], v[124:127]
	v_mfma_f32_16x16x32_bf16 v[120:123], v[182:185], v[232:235], v[120:123]
	v_mfma_f32_16x16x32_bf16 v[128:131], v[200:203], v[232:235], v[128:131]
	s_add_i32 s89, s89, 2
	s_add_u32 s26, s26, 0x100
	s_addc_u32 s27, s27, 0
	s_cmp_gt_u32 s89, 13
	s_barrier
	s_cbranch_scc0 .LBB0_973
	s_and_b64 vcc, exec, s[52:53]
	s_cbranch_vccz .LBB0_976
	s_barrier

.LBB0_1134:
	s_ashr_i32 s57, s56, 31
	s_lshl_b64 s[60:61], s[56:57], 19
	s_add_u32 s60, s42, s60
	s_addc_u32 s61, s43, s61
	s_and_b64 s[62:63], s[10:11], exec
	s_cselect_b32 s57, s61, s27
	s_cselect_b32 s79, s60, s26
	s_ashr_i32 s59, s58, 31
	s_lshl_b64 s[62:63], s[58:59], 19
	v_readlane_b32 s70, v254, 7
	v_readlane_b32 s71, v254, 8
	s_add_u32 s62, s70, s62
	s_addc_u32 s63, s71, s63
	s_and_b64 s[70:71], s[10:11], exec
	s_cselect_b32 s59, s63, s69
	s_cselect_b32 s80, s62, s68
	s_add_u32 s81, s68, 0x100
	v_lshl_add_u64 v[138:139], s[26:27], 0, v[132:133]
	s_addc_u32 s82, s69, 0
	s_mov_b32 s83, -2
	s_mov_b64 s[68:69], 0
	ds_read_b128 v[168:171], v145
	ds_read_b128 v[174:177], v146
	ds_read_b128 v[178:181], v147
	ds_read_b128 v[182:185], v148
	ds_read_b128 v[194:197], v149
	ds_read_b128 v[198:201], v150
	ds_read_b128 v[202:205], v151
	ds_read_b128 v[206:209], v152
	s_add_u32 s70, s26, s68
	s_addc_u32 s71, s27, s69
	s_add_u32 s70, s70, 0x100
	s_addc_u32 s71, s71, 0
	s_add_u32 s84, s81, s68
	s_addc_u32 s85, s82, s69
	s_cmpk_eq_i32 s68, 0x700
	s_cselect_b32 s85, s59, s85
	s_cselect_b32 s84, s80, s84
	s_cselect_b32 s71, s57, s71
	s_cselect_b32 s70, s79, s70
	v_lshl_add_u64 v[140:141], v[138:139], 0, s[68:69]
	v_lshl_add_u64 v[242:243], v[140:141], 0, s[22:23]
	s_add_i32 m0, s34, 0x8000
	s_mov_b64 s[86:87], 0x20080
	ds_read_b128 v[210:213], v153
	ds_read_b128 v[214:217], v153 offset:2048
	ds_read_b128 v[218:221], v154
	ds_read_b128 v[222:225], v154 offset:2048
	ds_read_b128 v[226:229], v153 offset:4096
	ds_read_b128 v[230:233], v153 offset:6144
	ds_read_b128 v[234:237], v154 offset:4096
	ds_read_b128 v[238:241], v154 offset:6144
	global_load_lds_dwordx4 v[242:243], off
	v_lshl_add_u64 v[242:243], v[140:141], 0, s[86:87]
	s_add_i32 m0, s34, 0xa000
	s_mov_b64 s[86:87], 0x60080
	global_load_lds_dwordx4 v[242:243], off
	v_lshl_add_u64 v[242:243], v[140:141], 0, s[24:25]
	s_add_i32 m0, s34, 0xc000
	v_lshl_add_u64 v[140:141], v[140:141], 0, s[86:87]
	global_load_lds_dwordx4 v[242:243], off
	s_add_i32 m0, s34, 0xe000
	s_nop 0
	global_load_lds_dwordx4 v[140:141], off
	s_waitcnt lgkmcnt(0)
	s_barrier
	v_mfma_f32_16x16x32_bf16 v[128:131], v[168:171], v[210:213], 0
	v_mfma_f32_16x16x32_bf16 v[124:127], v[178:181], v[210:213], 0
	v_mfma_f32_16x16x32_bf16 v[112:115], v[168:171], v[214:217], 0
	v_mfma_f32_16x16x32_bf16 v[108:111], v[178:181], v[214:217], 0
	v_mfma_f32_16x16x32_bf16 v[96:99], v[168:171], v[226:229], 0
	v_mfma_f32_16x16x32_bf16 v[92:95], v[178:181], v[226:229], 0
	v_mfma_f32_16x16x32_bf16 v[80:83], v[168:171], v[230:233], 0
	v_mfma_f32_16x16x32_bf16 v[76:79], v[178:181], v[230:233], 0
	v_mfma_f32_16x16x32_bf16 v[128:131], v[174:177], v[218:221], v[128:131]
	v_mfma_f32_16x16x32_bf16 v[124:127], v[182:185], v[218:221], v[124:127]
	v_mfma_f32_16x16x32_bf16 v[112:115], v[174:177], v[222:225], v[112:115]
	v_mfma_f32_16x16x32_bf16 v[108:111], v[182:185], v[222:225], v[108:111]
	v_mfma_f32_16x16x32_bf16 v[96:99], v[174:177], v[234:237], v[96:99]
	v_mfma_f32_16x16x32_bf16 v[92:95], v[182:185], v[234:237], v[92:95]
	v_mfma_f32_16x16x32_bf16 v[80:83], v[174:177], v[238:241], v[80:83]
	v_mfma_f32_16x16x32_bf16 v[76:79], v[182:185], v[238:241], v[76:79]
	v_mfma_f32_16x16x32_bf16 v[120:123], v[194:197], v[210:213], 0
	v_mfma_f32_16x16x32_bf16 v[116:119], v[202:205], v[210:213], 0
	v_mfma_f32_16x16x32_bf16 v[104:107], v[194:197], v[214:217], 0
	v_mfma_f32_16x16x32_bf16 v[100:103], v[202:205], v[214:217], 0
	v_mfma_f32_16x16x32_bf16 v[88:91], v[194:197], v[226:229], 0
	v_mfma_f32_16x16x32_bf16 v[84:87], v[202:205], v[226:229], 0
	v_mfma_f32_16x16x32_bf16 v[72:75], v[194:197], v[230:233], 0
	v_mfma_f32_16x16x32_bf16 v[68:71], v[202:205], v[230:233], 0
	v_mfma_f32_16x16x32_bf16 v[120:123], v[198:201], v[218:221], v[120:123]
	v_mfma_f32_16x16x32_bf16 v[116:119], v[206:209], v[218:221], v[116:119]
	v_mfma_f32_16x16x32_bf16 v[104:107], v[198:201], v[222:225], v[104:107]
	v_mfma_f32_16x16x32_bf16 v[100:103], v[206:209], v[222:225], v[100:103]
	v_mfma_f32_16x16x32_bf16 v[88:91], v[198:201], v[234:237], v[88:91]
	v_mfma_f32_16x16x32_bf16 v[84:87], v[206:209], v[234:237], v[84:87]
	v_mfma_f32_16x16x32_bf16 v[72:75], v[198:201], v[238:241], v[72:75]
	v_mfma_f32_16x16x32_bf16 v[68:71], v[206:209], v[238:241], v[68:71]
	s_barrier
	v_lshl_add_u64 v[140:141], s[84:85], 0, v[158:159]
	s_add_i32 s84, s67, s3
	s_mov_b32 m0, s84
	ds_read_b128 v[210:213], v153 offset:16384
	ds_read_b128 v[214:217], v153 offset:18432
	ds_read_b128 v[218:221], v154 offset:16384
	ds_read_b128 v[222:225], v154 offset:18432
	ds_read_b128 v[226:229], v153 offset:20480
	ds_read_b128 v[230:233], v153 offset:22528
	ds_read_b128 v[234:237], v154 offset:20480
	ds_read_b128 v[238:241], v154 offset:22528
	global_load_lds_dwordx4 v[140:141], off
	v_lshl_add_u64 v[242:243], v[140:141], 0, s[0:1]
	s_add_i32 m0, s84, 0x2000
	s_add_i32 s84, s72, s3
	global_load_lds_dwordx4 v[242:243], off
	v_lshl_add_u64 v[242:243], v[140:141], 0, s[12:13]
	s_mov_b32 m0, s84
	s_nop 0
	global_load_lds_dwordx4 v[242:243], off
	v_lshl_add_u64 v[242:243], v[140:141], 0, s[14:15]
	s_add_i32 m0, s84, 0x2000
	s_nop 0
	global_load_lds_dwordx4 v[242:243], off
	s_waitcnt vmcnt(4)
	s_waitcnt lgkmcnt(0)
	s_barrier
	v_mfma_f32_16x16x32_bf16 v[64:67], v[168:171], v[210:213], 0
	v_mfma_f32_16x16x32_bf16 v[60:63], v[178:181], v[210:213], 0
	v_mfma_f32_16x16x32_bf16 v[48:51], v[168:171], v[214:217], 0
	v_mfma_f32_16x16x32_bf16 v[44:47], v[178:181], v[214:217], 0
	v_mfma_f32_16x16x32_bf16 v[32:35], v[168:171], v[226:229], 0
	v_mfma_f32_16x16x32_bf16 v[28:31], v[178:181], v[226:229], 0
	v_mfma_f32_16x16x32_bf16 v[16:19], v[168:171], v[230:233], 0
	v_mfma_f32_16x16x32_bf16 v[12:15], v[178:181], v[230:233], 0
	v_mfma_f32_16x16x32_bf16 v[64:67], v[174:177], v[218:221], v[64:67]
	v_mfma_f32_16x16x32_bf16 v[60:63], v[182:185], v[218:221], v[60:63]
	v_mfma_f32_16x16x32_bf16 v[48:51], v[174:177], v[222:225], v[48:51]
	v_mfma_f32_16x16x32_bf16 v[44:47], v[182:185], v[222:225], v[44:47]
	v_mfma_f32_16x16x32_bf16 v[32:35], v[174:177], v[234:237], v[32:35]
	v_mfma_f32_16x16x32_bf16 v[28:31], v[182:185], v[234:237], v[28:31]
	v_mfma_f32_16x16x32_bf16 v[16:19], v[174:177], v[238:241], v[16:19]
	v_mfma_f32_16x16x32_bf16 v[12:15], v[182:185], v[238:241], v[12:15]
	v_mfma_f32_16x16x32_bf16 v[56:59], v[194:197], v[210:213], 0
	v_mfma_f32_16x16x32_bf16 v[52:55], v[202:205], v[210:213], 0
	v_mfma_f32_16x16x32_bf16 v[40:43], v[194:197], v[214:217], 0
	v_mfma_f32_16x16x32_bf16 v[36:39], v[202:205], v[214:217], 0
	v_mfma_f32_16x16x32_bf16 v[24:27], v[194:197], v[226:229], 0
	v_mfma_f32_16x16x32_bf16 v[20:23], v[202:205], v[226:229], 0
	v_mfma_f32_16x16x32_bf16 v[8:11], v[194:197], v[230:233], 0
	v_mfma_f32_16x16x32_bf16 v[4:7], v[202:205], v[230:233], 0
	v_mfma_f32_16x16x32_bf16 v[56:59], v[198:201], v[218:221], v[56:59]
	v_mfma_f32_16x16x32_bf16 v[52:55], v[206:209], v[218:221], v[52:55]
	v_mfma_f32_16x16x32_bf16 v[40:43], v[198:201], v[222:225], v[40:43]
	v_mfma_f32_16x16x32_bf16 v[36:39], v[206:209], v[222:225], v[36:39]
	v_mfma_f32_16x16x32_bf16 v[24:27], v[198:201], v[234:237], v[24:27]
	v_mfma_f32_16x16x32_bf16 v[20:23], v[206:209], v[234:237], v[20:23]
	v_mfma_f32_16x16x32_bf16 v[8:11], v[198:201], v[238:241], v[8:11]
	v_mfma_f32_16x16x32_bf16 v[4:7], v[206:209], v[238:241], v[4:7]
	s_barrier
	ds_read_b128 v[168:171], v163
	ds_read_b128 v[174:177], v164
	ds_read_b128 v[178:181], v155
	ds_read_b128 v[182:185], v160
	ds_read_b128 v[194:197], v165
	ds_read_b128 v[198:201], v166
	ds_read_b128 v[202:205], v161
	ds_read_b128 v[206:209], v162
	s_mov_b32 m0, s34
	v_lshl_add_u64 v[242:243], s[70:71], 0, v[0:1]
	ds_read_b128 v[210:213], v153 offset:32768
	ds_read_b128 v[214:217], v153 offset:34816
	ds_read_b128 v[218:221], v154 offset:32768
	ds_read_b128 v[222:225], v154 offset:34816
	ds_read_b128 v[226:229], v153 offset:36864
	ds_read_b128 v[230:233], v153 offset:38912
	ds_read_b128 v[234:237], v154 offset:36864
	ds_read_b128 v[238:241], v154 offset:38912
	global_load_lds_dwordx4 v[242:243], off
	v_lshl_add_u64 v[244:245], v[242:243], 0, s[16:17]
	s_mov_b32 m0, s35
	s_nop 0
	global_load_lds_dwordx4 v[244:245], off
	v_lshl_add_u64 v[244:245], v[242:243], 0, s[0:1]
	s_mov_b32 m0, s38
	v_lshl_add_u64 v[242:243], v[242:243], 0, s[18:19]
	global_load_lds_dwordx4 v[244:245], off
	s_mov_b32 m0, s39
	s_nop 0
	global_load_lds_dwordx4 v[242:243], off
	s_waitcnt vmcnt(8)
	s_waitcnt lgkmcnt(0)
	s_barrier
	v_mfma_f32_16x16x32_bf16 v[128:131], v[168:171], v[210:213], v[128:131]
	v_mfma_f32_16x16x32_bf16 v[124:127], v[178:181], v[210:213], v[124:127]
	v_mfma_f32_16x16x32_bf16 v[112:115], v[168:171], v[214:217], v[112:115]
	v_mfma_f32_16x16x32_bf16 v[108:111], v[178:181], v[214:217], v[108:111]
	v_mfma_f32_16x16x32_bf16 v[96:99], v[168:171], v[226:229], v[96:99]
	v_mfma_f32_16x16x32_bf16 v[92:95], v[178:181], v[226:229], v[92:95]
	v_mfma_f32_16x16x32_bf16 v[80:83], v[168:171], v[230:233], v[80:83]
	v_mfma_f32_16x16x32_bf16 v[76:79], v[178:181], v[230:233], v[76:79]
	v_mfma_f32_16x16x32_bf16 v[128:131], v[174:177], v[218:221], v[128:131]
	v_mfma_f32_16x16x32_bf16 v[124:127], v[182:185], v[218:221], v[124:127]
	v_mfma_f32_16x16x32_bf16 v[112:115], v[174:177], v[222:225], v[112:115]
	v_mfma_f32_16x16x32_bf16 v[108:111], v[182:185], v[222:225], v[108:111]
	v_mfma_f32_16x16x32_bf16 v[96:99], v[174:177], v[234:237], v[96:99]
	v_mfma_f32_16x16x32_bf16 v[92:95], v[182:185], v[234:237], v[92:95]
	v_mfma_f32_16x16x32_bf16 v[80:83], v[174:177], v[238:241], v[80:83]
	v_mfma_f32_16x16x32_bf16 v[76:79], v[182:185], v[238:241], v[76:79]
	v_mfma_f32_16x16x32_bf16 v[120:123], v[194:197], v[210:213], v[120:123]
	v_mfma_f32_16x16x32_bf16 v[116:119], v[202:205], v[210:213], v[116:119]
	v_mfma_f32_16x16x32_bf16 v[104:107], v[194:197], v[214:217], v[104:107]
	v_mfma_f32_16x16x32_bf16 v[100:103], v[202:205], v[214:217], v[100:103]
	v_mfma_f32_16x16x32_bf16 v[88:91], v[194:197], v[226:229], v[88:91]
	v_mfma_f32_16x16x32_bf16 v[84:87], v[202:205], v[226:229], v[84:87]
	v_mfma_f32_16x16x32_bf16 v[72:75], v[194:197], v[230:233], v[72:75]
	v_mfma_f32_16x16x32_bf16 v[68:71], v[202:205], v[230:233], v[68:71]
	v_mfma_f32_16x16x32_bf16 v[120:123], v[198:201], v[218:221], v[120:123]
	v_mfma_f32_16x16x32_bf16 v[116:119], v[206:209], v[218:221], v[116:119]
	v_mfma_f32_16x16x32_bf16 v[104:107], v[198:201], v[222:225], v[104:107]
	v_mfma_f32_16x16x32_bf16 v[100:103], v[206:209], v[222:225], v[100:103]
	v_mfma_f32_16x16x32_bf16 v[88:91], v[198:201], v[234:237], v[88:91]
	v_mfma_f32_16x16x32_bf16 v[84:87], v[206:209], v[234:237], v[84:87]
	v_mfma_f32_16x16x32_bf16 v[72:75], v[198:201], v[238:241], v[72:75]
	v_mfma_f32_16x16x32_bf16 v[68:71], v[206:209], v[238:241], v[68:71]
	s_barrier
	s_add_i32 s70, s73, s3
	v_lshl_add_u64 v[242:243], v[140:141], 0, s[22:23]
	s_mov_b32 m0, s70
	ds_read_b128 v[210:213], v153 offset:49152
	ds_read_b128 v[214:217], v153 offset:51200
	ds_read_b128 v[218:221], v154 offset:49152
	ds_read_b128 v[222:225], v154 offset:51200
	ds_read_b128 v[226:229], v153 offset:53248
	ds_read_b128 v[230:233], v153 offset:55296
	ds_read_b128 v[234:237], v154 offset:53248
	ds_read_b128 v[238:241], v154 offset:55296
	global_load_lds_dwordx4 v[242:243], off
	v_lshl_add_u64 v[242:243], v[140:141], 0, s[24:25]
	s_add_i32 m0, s70, 0x2000
	s_add_i32 s70, s77, s3
	global_load_lds_dwordx4 v[242:243], off
	v_lshl_add_u64 v[242:243], v[140:141], 0, s[28:29]
	s_mov_b32 m0, s70
	v_lshl_add_u64 v[140:141], v[140:141], 0, s[36:37]
	global_load_lds_dwordx4 v[242:243], off
	s_add_i32 m0, s70, 0x2000
	s_nop 0
	global_load_lds_dwordx4 v[140:141], off
	s_waitcnt vmcnt(4)
	s_waitcnt lgkmcnt(0)
	s_barrier
	v_mfma_f32_16x16x32_bf16 v[64:67], v[168:171], v[210:213], v[64:67]
	v_mfma_f32_16x16x32_bf16 v[60:63], v[178:181], v[210:213], v[60:63]
	v_mfma_f32_16x16x32_bf16 v[48:51], v[168:171], v[214:217], v[48:51]
	v_mfma_f32_16x16x32_bf16 v[44:47], v[178:181], v[214:217], v[44:47]
	v_mfma_f32_16x16x32_bf16 v[32:35], v[168:171], v[226:229], v[32:35]
	v_mfma_f32_16x16x32_bf16 v[28:31], v[178:181], v[226:229], v[28:31]
	v_mfma_f32_16x16x32_bf16 v[16:19], v[168:171], v[230:233], v[16:19]
	v_mfma_f32_16x16x32_bf16 v[12:15], v[178:181], v[230:233], v[12:15]
	v_mfma_f32_16x16x32_bf16 v[64:67], v[174:177], v[218:221], v[64:67]
	v_mfma_f32_16x16x32_bf16 v[60:63], v[182:185], v[218:221], v[60:63]
	v_mfma_f32_16x16x32_bf16 v[48:51], v[174:177], v[222:225], v[48:51]
	v_mfma_f32_16x16x32_bf16 v[44:47], v[182:185], v[222:225], v[44:47]
	v_mfma_f32_16x16x32_bf16 v[32:35], v[174:177], v[234:237], v[32:35]
	v_mfma_f32_16x16x32_bf16 v[28:31], v[182:185], v[234:237], v[28:31]
	v_mfma_f32_16x16x32_bf16 v[16:19], v[174:177], v[238:241], v[16:19]
	v_mfma_f32_16x16x32_bf16 v[12:15], v[182:185], v[238:241], v[12:15]
	v_mfma_f32_16x16x32_bf16 v[56:59], v[194:197], v[210:213], v[56:59]
	v_mfma_f32_16x16x32_bf16 v[52:55], v[202:205], v[210:213], v[52:55]
	v_mfma_f32_16x16x32_bf16 v[40:43], v[194:197], v[214:217], v[40:43]
	v_mfma_f32_16x16x32_bf16 v[36:39], v[202:205], v[214:217], v[36:39]
	v_mfma_f32_16x16x32_bf16 v[24:27], v[194:197], v[226:229], v[24:27]
	v_mfma_f32_16x16x32_bf16 v[20:23], v[202:205], v[226:229], v[20:23]
	v_mfma_f32_16x16x32_bf16 v[8:11], v[194:197], v[230:233], v[8:11]
	v_mfma_f32_16x16x32_bf16 v[4:7], v[202:205], v[230:233], v[4:7]
	v_mfma_f32_16x16x32_bf16 v[56:59], v[198:201], v[218:221], v[56:59]
	v_mfma_f32_16x16x32_bf16 v[52:55], v[206:209], v[218:221], v[52:55]
	v_mfma_f32_16x16x32_bf16 v[40:43], v[198:201], v[222:225], v[40:43]
	v_mfma_f32_16x16x32_bf16 v[36:39], v[206:209], v[222:225], v[36:39]
	v_mfma_f32_16x16x32_bf16 v[24:27], v[198:201], v[234:237], v[24:27]
	v_mfma_f32_16x16x32_bf16 v[20:23], v[206:209], v[234:237], v[20:23]
	v_mfma_f32_16x16x32_bf16 v[8:11], v[198:201], v[238:241], v[8:11]
	v_mfma_f32_16x16x32_bf16 v[4:7], v[206:209], v[238:241], v[4:7]
	s_add_i32 s83, s83, 2
	s_add_u32 s68, s68, 0x100
	s_addc_u32 s69, s69, 0
	s_cmp_gt_u32 s83, 13
	s_barrier
.LBB0_1135:
	ds_read_b128 v[168:171], v145
	ds_read_b128 v[174:177], v146
	ds_read_b128 v[178:181], v147
	ds_read_b128 v[182:185], v148
	ds_read_b128 v[194:197], v149
	ds_read_b128 v[198:201], v150
	ds_read_b128 v[202:205], v151
	ds_read_b128 v[206:209], v152
	s_add_u32 s70, s26, s68
	s_addc_u32 s71, s27, s69
	s_add_u32 s70, s70, 0x100
	s_addc_u32 s71, s71, 0
	s_add_u32 s84, s81, s68
	s_addc_u32 s85, s82, s69
	s_cmpk_eq_i32 s68, 0x700
	s_cselect_b32 s85, s59, s85
	s_cselect_b32 s84, s80, s84
	s_cselect_b32 s71, s57, s71
	s_cselect_b32 s70, s79, s70
	v_lshl_add_u64 v[140:141], v[138:139], 0, s[68:69]
	v_lshl_add_u64 v[242:243], v[140:141], 0, s[22:23]
	s_add_i32 m0, s34, 0x8000
	s_mov_b64 s[86:87], 0x20080
	ds_read_b128 v[210:213], v153
	ds_read_b128 v[214:217], v153 offset:2048
	ds_read_b128 v[218:221], v154
	ds_read_b128 v[222:225], v154 offset:2048
	ds_read_b128 v[226:229], v153 offset:4096
	ds_read_b128 v[230:233], v153 offset:6144
	ds_read_b128 v[234:237], v154 offset:4096
	ds_read_b128 v[238:241], v154 offset:6144
	global_load_lds_dwordx4 v[242:243], off
	v_lshl_add_u64 v[242:243], v[140:141], 0, s[86:87]
	s_add_i32 m0, s34, 0xa000
	s_mov_b64 s[86:87], 0x60080
	global_load_lds_dwordx4 v[242:243], off
	v_lshl_add_u64 v[242:243], v[140:141], 0, s[24:25]
	s_add_i32 m0, s34, 0xc000
	v_lshl_add_u64 v[140:141], v[140:141], 0, s[86:87]
	global_load_lds_dwordx4 v[242:243], off
	s_add_i32 m0, s34, 0xe000
	s_nop 0
	global_load_lds_dwordx4 v[140:141], off
	s_waitcnt vmcnt(8)
	s_waitcnt lgkmcnt(0)
	s_barrier
	v_mfma_f32_16x16x32_bf16 v[128:131], v[168:171], v[210:213], v[128:131]
	v_mfma_f32_16x16x32_bf16 v[124:127], v[178:181], v[210:213], v[124:127]
	v_mfma_f32_16x16x32_bf16 v[112:115], v[168:171], v[214:217], v[112:115]
	v_mfma_f32_16x16x32_bf16 v[108:111], v[178:181], v[214:217], v[108:111]
	v_mfma_f32_16x16x32_bf16 v[96:99], v[168:171], v[226:229], v[96:99]
	v_mfma_f32_16x16x32_bf16 v[92:95], v[178:181], v[226:229], v[92:95]
	v_mfma_f32_16x16x32_bf16 v[80:83], v[168:171], v[230:233], v[80:83]
	v_mfma_f32_16x16x32_bf16 v[76:79], v[178:181], v[230:233], v[76:79]
	v_mfma_f32_16x16x32_bf16 v[128:131], v[174:177], v[218:221], v[128:131]
	v_mfma_f32_16x16x32_bf16 v[124:127], v[182:185], v[218:221], v[124:127]
	v_mfma_f32_16x16x32_bf16 v[112:115], v[174:177], v[222:225], v[112:115]
	v_mfma_f32_16x16x32_bf16 v[108:111], v[182:185], v[222:225], v[108:111]
	v_mfma_f32_16x16x32_bf16 v[96:99], v[174:177], v[234:237], v[96:99]
	v_mfma_f32_16x16x32_bf16 v[92:95], v[182:185], v[234:237], v[92:95]
	v_mfma_f32_16x16x32_bf16 v[80:83], v[174:177], v[238:241], v[80:83]
	v_mfma_f32_16x16x32_bf16 v[76:79], v[182:185], v[238:241], v[76:79]
	v_mfma_f32_16x16x32_bf16 v[120:123], v[194:197], v[210:213], v[120:123]
	v_mfma_f32_16x16x32_bf16 v[116:119], v[202:205], v[210:213], v[116:119]
	v_mfma_f32_16x16x32_bf16 v[104:107], v[194:197], v[214:217], v[104:107]
	v_mfma_f32_16x16x32_bf16 v[100:103], v[202:205], v[214:217], v[100:103]
	v_mfma_f32_16x16x32_bf16 v[88:91], v[194:197], v[226:229], v[88:91]
	v_mfma_f32_16x16x32_bf16 v[84:87], v[202:205], v[226:229], v[84:87]
	v_mfma_f32_16x16x32_bf16 v[72:75], v[194:197], v[230:233], v[72:75]
	v_mfma_f32_16x16x32_bf16 v[68:71], v[202:205], v[230:233], v[68:71]
	v_mfma_f32_16x16x32_bf16 v[120:123], v[198:201], v[218:221], v[120:123]
	v_mfma_f32_16x16x32_bf16 v[116:119], v[206:209], v[218:221], v[116:119]
	v_mfma_f32_16x16x32_bf16 v[104:107], v[198:201], v[222:225], v[104:107]
	v_mfma_f32_16x16x32_bf16 v[100:103], v[206:209], v[222:225], v[100:103]
	v_mfma_f32_16x16x32_bf16 v[88:91], v[198:201], v[234:237], v[88:91]
	v_mfma_f32_16x16x32_bf16 v[84:87], v[206:209], v[234:237], v[84:87]
	v_mfma_f32_16x16x32_bf16 v[72:75], v[198:201], v[238:241], v[72:75]
	v_mfma_f32_16x16x32_bf16 v[68:71], v[206:209], v[238:241], v[68:71]
	s_barrier
	v_lshl_add_u64 v[140:141], s[84:85], 0, v[158:159]
	s_add_i32 s84, s67, s3
	s_mov_b32 m0, s84
	ds_read_b128 v[210:213], v153 offset:16384
	ds_read_b128 v[214:217], v153 offset:18432
	ds_read_b128 v[218:221], v154 offset:16384
	ds_read_b128 v[222:225], v154 offset:18432
	ds_read_b128 v[226:229], v153 offset:20480
	ds_read_b128 v[230:233], v153 offset:22528
	ds_read_b128 v[234:237], v154 offset:20480
	ds_read_b128 v[238:241], v154 offset:22528
	global_load_lds_dwordx4 v[140:141], off
	v_lshl_add_u64 v[242:243], v[140:141], 0, s[0:1]
	s_add_i32 m0, s84, 0x2000
	s_add_i32 s84, s72, s3
	global_load_lds_dwordx4 v[242:243], off
	v_lshl_add_u64 v[242:243], v[140:141], 0, s[12:13]
	s_mov_b32 m0, s84
	s_nop 0
	global_load_lds_dwordx4 v[242:243], off
	v_lshl_add_u64 v[242:243], v[140:141], 0, s[14:15]
	s_add_i32 m0, s84, 0x2000
	s_nop 0
	global_load_lds_dwordx4 v[242:243], off
	s_waitcnt vmcnt(4)
	s_waitcnt lgkmcnt(0)
	s_barrier
	v_mfma_f32_16x16x32_bf16 v[64:67], v[168:171], v[210:213], v[64:67]
	v_mfma_f32_16x16x32_bf16 v[60:63], v[178:181], v[210:213], v[60:63]
	v_mfma_f32_16x16x32_bf16 v[48:51], v[168:171], v[214:217], v[48:51]
	v_mfma_f32_16x16x32_bf16 v[44:47], v[178:181], v[214:217], v[44:47]
	v_mfma_f32_16x16x32_bf16 v[32:35], v[168:171], v[226:229], v[32:35]
	v_mfma_f32_16x16x32_bf16 v[28:31], v[178:181], v[226:229], v[28:31]
	v_mfma_f32_16x16x32_bf16 v[16:19], v[168:171], v[230:233], v[16:19]
	v_mfma_f32_16x16x32_bf16 v[12:15], v[178:181], v[230:233], v[12:15]
	v_mfma_f32_16x16x32_bf16 v[64:67], v[174:177], v[218:221], v[64:67]
	v_mfma_f32_16x16x32_bf16 v[60:63], v[182:185], v[218:221], v[60:63]
	v_mfma_f32_16x16x32_bf16 v[48:51], v[174:177], v[222:225], v[48:51]
	v_mfma_f32_16x16x32_bf16 v[44:47], v[182:185], v[222:225], v[44:47]
	v_mfma_f32_16x16x32_bf16 v[32:35], v[174:177], v[234:237], v[32:35]
	v_mfma_f32_16x16x32_bf16 v[28:31], v[182:185], v[234:237], v[28:31]
	v_mfma_f32_16x16x32_bf16 v[16:19], v[174:177], v[238:241], v[16:19]
	v_mfma_f32_16x16x32_bf16 v[12:15], v[182:185], v[238:241], v[12:15]
	v_mfma_f32_16x16x32_bf16 v[56:59], v[194:197], v[210:213], v[56:59]
	v_mfma_f32_16x16x32_bf16 v[52:55], v[202:205], v[210:213], v[52:55]
	v_mfma_f32_16x16x32_bf16 v[40:43], v[194:197], v[214:217], v[40:43]
	v_mfma_f32_16x16x32_bf16 v[36:39], v[202:205], v[214:217], v[36:39]
	v_mfma_f32_16x16x32_bf16 v[24:27], v[194:197], v[226:229], v[24:27]
	v_mfma_f32_16x16x32_bf16 v[20:23], v[202:205], v[226:229], v[20:23]
	v_mfma_f32_16x16x32_bf16 v[8:11], v[194:197], v[230:233], v[8:11]
	v_mfma_f32_16x16x32_bf16 v[4:7], v[202:205], v[230:233], v[4:7]
	v_mfma_f32_16x16x32_bf16 v[56:59], v[198:201], v[218:221], v[56:59]
	v_mfma_f32_16x16x32_bf16 v[52:55], v[206:209], v[218:221], v[52:55]
	v_mfma_f32_16x16x32_bf16 v[40:43], v[198:201], v[222:225], v[40:43]
	v_mfma_f32_16x16x32_bf16 v[36:39], v[206:209], v[222:225], v[36:39]
	v_mfma_f32_16x16x32_bf16 v[24:27], v[198:201], v[234:237], v[24:27]
	v_mfma_f32_16x16x32_bf16 v[20:23], v[206:209], v[234:237], v[20:23]
	v_mfma_f32_16x16x32_bf16 v[8:11], v[198:201], v[238:241], v[8:11]
	v_mfma_f32_16x16x32_bf16 v[4:7], v[206:209], v[238:241], v[4:7]
	s_barrier
	ds_read_b128 v[168:171], v163
	ds_read_b128 v[174:177], v164
	ds_read_b128 v[178:181], v155
	ds_read_b128 v[182:185], v160
	ds_read_b128 v[194:197], v165
	ds_read_b128 v[198:201], v166
	ds_read_b128 v[202:205], v161
	ds_read_b128 v[206:209], v162
	s_mov_b32 m0, s34
	v_lshl_add_u64 v[242:243], s[70:71], 0, v[0:1]
	ds_read_b128 v[210:213], v153 offset:32768
	ds_read_b128 v[214:217], v153 offset:34816
	ds_read_b128 v[218:221], v154 offset:32768
	ds_read_b128 v[222:225], v154 offset:34816
	ds_read_b128 v[226:229], v153 offset:36864
	ds_read_b128 v[230:233], v153 offset:38912
	ds_read_b128 v[234:237], v154 offset:36864
	ds_read_b128 v[238:241], v154 offset:38912
	global_load_lds_dwordx4 v[242:243], off
	v_lshl_add_u64 v[244:245], v[242:243], 0, s[16:17]
	s_mov_b32 m0, s35
	s_nop 0
	global_load_lds_dwordx4 v[244:245], off
	v_lshl_add_u64 v[244:245], v[242:243], 0, s[0:1]
	s_mov_b32 m0, s38
	v_lshl_add_u64 v[242:243], v[242:243], 0, s[18:19]
	global_load_lds_dwordx4 v[244:245], off
	s_mov_b32 m0, s39
	s_nop 0
	global_load_lds_dwordx4 v[242:243], off
	s_waitcnt vmcnt(8)
	s_waitcnt lgkmcnt(0)
	s_barrier
	v_mfma_f32_16x16x32_bf16 v[128:131], v[168:171], v[210:213], v[128:131]
	v_mfma_f32_16x16x32_bf16 v[124:127], v[178:181], v[210:213], v[124:127]
	v_mfma_f32_16x16x32_bf16 v[112:115], v[168:171], v[214:217], v[112:115]
	v_mfma_f32_16x16x32_bf16 v[108:111], v[178:181], v[214:217], v[108:111]
	v_mfma_f32_16x16x32_bf16 v[96:99], v[168:171], v[226:229], v[96:99]
	v_mfma_f32_16x16x32_bf16 v[92:95], v[178:181], v[226:229], v[92:95]
	v_mfma_f32_16x16x32_bf16 v[80:83], v[168:171], v[230:233], v[80:83]
	v_mfma_f32_16x16x32_bf16 v[76:79], v[178:181], v[230:233], v[76:79]
	v_mfma_f32_16x16x32_bf16 v[128:131], v[174:177], v[218:221], v[128:131]
	v_mfma_f32_16x16x32_bf16 v[124:127], v[182:185], v[218:221], v[124:127]
	v_mfma_f32_16x16x32_bf16 v[112:115], v[174:177], v[222:225], v[112:115]
	v_mfma_f32_16x16x32_bf16 v[108:111], v[182:185], v[222:225], v[108:111]
	v_mfma_f32_16x16x32_bf16 v[96:99], v[174:177], v[234:237], v[96:99]
	v_mfma_f32_16x16x32_bf16 v[92:95], v[182:185], v[234:237], v[92:95]
	v_mfma_f32_16x16x32_bf16 v[80:83], v[174:177], v[238:241], v[80:83]
	v_mfma_f32_16x16x32_bf16 v[76:79], v[182:185], v[238:241], v[76:79]
	v_mfma_f32_16x16x32_bf16 v[120:123], v[194:197], v[210:213], v[120:123]
	v_mfma_f32_16x16x32_bf16 v[116:119], v[202:205], v[210:213], v[116:119]
	v_mfma_f32_16x16x32_bf16 v[104:107], v[194:197], v[214:217], v[104:107]
	v_mfma_f32_16x16x32_bf16 v[100:103], v[202:205], v[214:217], v[100:103]
	v_mfma_f32_16x16x32_bf16 v[88:91], v[194:197], v[226:229], v[88:91]
	v_mfma_f32_16x16x32_bf16 v[84:87], v[202:205], v[226:229], v[84:87]
	v_mfma_f32_16x16x32_bf16 v[72:75], v[194:197], v[230:233], v[72:75]
	v_mfma_f32_16x16x32_bf16 v[68:71], v[202:205], v[230:233], v[68:71]
	v_mfma_f32_16x16x32_bf16 v[120:123], v[198:201], v[218:221], v[120:123]
	v_mfma_f32_16x16x32_bf16 v[116:119], v[206:209], v[218:221], v[116:119]
	v_mfma_f32_16x16x32_bf16 v[104:107], v[198:201], v[222:225], v[104:107]
	v_mfma_f32_16x16x32_bf16 v[100:103], v[206:209], v[222:225], v[100:103]
	v_mfma_f32_16x16x32_bf16 v[88:91], v[198:201], v[234:237], v[88:91]
	v_mfma_f32_16x16x32_bf16 v[84:87], v[206:209], v[234:237], v[84:87]
	v_mfma_f32_16x16x32_bf16 v[72:75], v[198:201], v[238:241], v[72:75]
	v_mfma_f32_16x16x32_bf16 v[68:71], v[206:209], v[238:241], v[68:71]
	s_barrier
	s_add_i32 s70, s73, s3
	v_lshl_add_u64 v[242:243], v[140:141], 0, s[22:23]
	s_mov_b32 m0, s70
	ds_read_b128 v[210:213], v153 offset:49152
	ds_read_b128 v[214:217], v153 offset:51200
	ds_read_b128 v[218:221], v154 offset:49152
	ds_read_b128 v[222:225], v154 offset:51200
	ds_read_b128 v[226:229], v153 offset:53248
	ds_read_b128 v[230:233], v153 offset:55296
	ds_read_b128 v[234:237], v154 offset:53248
	ds_read_b128 v[238:241], v154 offset:55296
	global_load_lds_dwordx4 v[242:243], off
	v_lshl_add_u64 v[242:243], v[140:141], 0, s[24:25]
	s_add_i32 m0, s70, 0x2000
	s_add_i32 s70, s77, s3
	global_load_lds_dwordx4 v[242:243], off
	v_lshl_add_u64 v[242:243], v[140:141], 0, s[28:29]
	s_mov_b32 m0, s70
	v_lshl_add_u64 v[140:141], v[140:141], 0, s[36:37]
	global_load_lds_dwordx4 v[242:243], off
	s_add_i32 m0, s70, 0x2000
	s_nop 0
	global_load_lds_dwordx4 v[140:141], off
	s_waitcnt vmcnt(4)
	s_waitcnt lgkmcnt(0)
	s_barrier
	v_mfma_f32_16x16x32_bf16 v[64:67], v[168:171], v[210:213], v[64:67]
	v_mfma_f32_16x16x32_bf16 v[60:63], v[178:181], v[210:213], v[60:63]
	v_mfma_f32_16x16x32_bf16 v[48:51], v[168:171], v[214:217], v[48:51]
	v_mfma_f32_16x16x32_bf16 v[44:47], v[178:181], v[214:217], v[44:47]
	v_mfma_f32_16x16x32_bf16 v[32:35], v[168:171], v[226:229], v[32:35]
	v_mfma_f32_16x16x32_bf16 v[28:31], v[178:181], v[226:229], v[28:31]
	v_mfma_f32_16x16x32_bf16 v[16:19], v[168:171], v[230:233], v[16:19]
	v_mfma_f32_16x16x32_bf16 v[12:15], v[178:181], v[230:233], v[12:15]
	v_mfma_f32_16x16x32_bf16 v[64:67], v[174:177], v[218:221], v[64:67]
	v_mfma_f32_16x16x32_bf16 v[60:63], v[182:185], v[218:221], v[60:63]
	v_mfma_f32_16x16x32_bf16 v[48:51], v[174:177], v[222:225], v[48:51]
	v_mfma_f32_16x16x32_bf16 v[44:47], v[182:185], v[222:225], v[44:47]
	v_mfma_f32_16x16x32_bf16 v[32:35], v[174:177], v[234:237], v[32:35]
	v_mfma_f32_16x16x32_bf16 v[28:31], v[182:185], v[234:237], v[28:31]
	v_mfma_f32_16x16x32_bf16 v[16:19], v[174:177], v[238:241], v[16:19]
	v_mfma_f32_16x16x32_bf16 v[12:15], v[182:185], v[238:241], v[12:15]
	v_mfma_f32_16x16x32_bf16 v[56:59], v[194:197], v[210:213], v[56:59]
	v_mfma_f32_16x16x32_bf16 v[52:55], v[202:205], v[210:213], v[52:55]
	v_mfma_f32_16x16x32_bf16 v[40:43], v[194:197], v[214:217], v[40:43]
	v_mfma_f32_16x16x32_bf16 v[36:39], v[202:205], v[214:217], v[36:39]
	v_mfma_f32_16x16x32_bf16 v[24:27], v[194:197], v[226:229], v[24:27]
	v_mfma_f32_16x16x32_bf16 v[20:23], v[202:205], v[226:229], v[20:23]
	v_mfma_f32_16x16x32_bf16 v[8:11], v[194:197], v[230:233], v[8:11]
	v_mfma_f32_16x16x32_bf16 v[4:7], v[202:205], v[230:233], v[4:7]
	v_mfma_f32_16x16x32_bf16 v[56:59], v[198:201], v[218:221], v[56:59]
	v_mfma_f32_16x16x32_bf16 v[52:55], v[206:209], v[218:221], v[52:55]
	v_mfma_f32_16x16x32_bf16 v[40:43], v[198:201], v[222:225], v[40:43]
	v_mfma_f32_16x16x32_bf16 v[36:39], v[206:209], v[222:225], v[36:39]
	v_mfma_f32_16x16x32_bf16 v[24:27], v[198:201], v[234:237], v[24:27]
	v_mfma_f32_16x16x32_bf16 v[20:23], v[206:209], v[234:237], v[20:23]
	v_mfma_f32_16x16x32_bf16 v[8:11], v[198:201], v[238:241], v[8:11]
	v_mfma_f32_16x16x32_bf16 v[4:7], v[206:209], v[238:241], v[4:7]
	s_add_i32 s83, s83, 2
	s_add_u32 s68, s68, 0x100
	s_addc_u32 s69, s69, 0
	s_cmp_gt_u32 s83, 13
	s_barrier
	s_cbranch_scc0 .LBB0_1135
	s_and_b64 vcc, exec, s[40:41]
	s_cbranch_vccz .LBB0_1138
	s_barrier

.LBB0_1371:
	v_add_u32_e32 v147, s64, v143
	v_add_u32_e32 v152, s64, v144
	ds_read_b128 v[148:151], v147
	ds_read_b128 v[152:155], v152
	v_add_u32_e32 v147, s65, v143
	v_add_u32_e32 v162, s65, v144
	s_add_u32 s58, s18, s56
	ds_read_b128 v[158:161], v147
	ds_read_b128 v[162:165], v162
	v_add_u32_e32 v147, s66, v143
	s_addc_u32 s59, s19, s57
	v_add_u32_e32 v166, s66, v144
	ds_read_b128 v[170:173], v147
	ds_read_b128 v[174:177], v166
	v_add_u32_e32 v147, s67, v143
	s_add_u32 s58, s58, 0x100
	v_add_u32_e32 v166, s67, v144
	ds_read_b128 v[178:181], v147
	ds_read_b128 v[182:185], v166
	s_addc_u32 s59, s59, 0
	s_add_u32 s78, s53, s56
	s_addc_u32 s79, s72, s57
	s_cmpk_eq_i32 s56, 0x1f00
	s_cselect_b32 s79, s49, s79
	s_cselect_b32 s78, s76, s78
	s_cselect_b32 s59, s51, s59
	s_cselect_b32 s58, s73, s58
	v_lshl_add_u64 v[166:167], v[140:141], 0, s[56:57]
	v_lshl_add_u64 v[218:219], v[166:167], 0, s[24:25]
	s_add_i32 m0, s35, 0x8000
	ds_read_b128 v[186:189], v145
	ds_read_b128 v[190:193], v145 offset:2048
	ds_read_b128 v[194:197], v146
	ds_read_b128 v[198:201], v146 offset:2048
	ds_read_b128 v[202:205], v145 offset:4096
	ds_read_b128 v[206:209], v145 offset:6144
	ds_read_b128 v[210:213], v146 offset:4096
	ds_read_b128 v[214:217], v146 offset:6144
	global_load_lds_dwordx4 v[218:219], off
	v_lshl_add_u64 v[218:219], v[166:167], 0, s[44:45]
	s_add_i32 m0, s35, 0xa000
	s_nop 0
	global_load_lds_dwordx4 v[218:219], off
	v_lshl_add_u64 v[218:219], v[166:167], 0, s[28:29]
	s_add_i32 m0, s35, 0xc000
	v_lshl_add_u64 v[166:167], v[166:167], 0, s[46:47]
	global_load_lds_dwordx4 v[218:219], off
	s_add_i32 m0, s35, 0xe000
	s_nop 0
	global_load_lds_dwordx4 v[166:167], off
	s_waitcnt vmcnt(8)
	s_waitcnt lgkmcnt(0)
	s_barrier
	v_mfma_f32_16x16x32_bf16 v[128:131], v[148:151], v[186:189], v[128:131]
	v_mfma_f32_16x16x32_bf16 v[124:127], v[158:161], v[186:189], v[124:127]
	v_mfma_f32_16x16x32_bf16 v[112:115], v[148:151], v[190:193], v[112:115]
	v_mfma_f32_16x16x32_bf16 v[108:111], v[158:161], v[190:193], v[108:111]
	v_mfma_f32_16x16x32_bf16 v[96:99], v[148:151], v[202:205], v[96:99]
	v_mfma_f32_16x16x32_bf16 v[92:95], v[158:161], v[202:205], v[92:95]
	v_mfma_f32_16x16x32_bf16 v[80:83], v[148:151], v[206:209], v[80:83]
	v_mfma_f32_16x16x32_bf16 v[76:79], v[158:161], v[206:209], v[76:79]
	v_mfma_f32_16x16x32_bf16 v[128:131], v[152:155], v[194:197], v[128:131]
	v_mfma_f32_16x16x32_bf16 v[124:127], v[162:165], v[194:197], v[124:127]
	v_mfma_f32_16x16x32_bf16 v[112:115], v[152:155], v[198:201], v[112:115]
	v_mfma_f32_16x16x32_bf16 v[108:111], v[162:165], v[198:201], v[108:111]
	v_mfma_f32_16x16x32_bf16 v[96:99], v[152:155], v[210:213], v[96:99]
	v_mfma_f32_16x16x32_bf16 v[92:95], v[162:165], v[210:213], v[92:95]
	v_mfma_f32_16x16x32_bf16 v[80:83], v[152:155], v[214:217], v[80:83]
	v_mfma_f32_16x16x32_bf16 v[76:79], v[162:165], v[214:217], v[76:79]
	v_mfma_f32_16x16x32_bf16 v[120:123], v[170:173], v[186:189], v[120:123]
	v_mfma_f32_16x16x32_bf16 v[116:119], v[178:181], v[186:189], v[116:119]
	v_mfma_f32_16x16x32_bf16 v[104:107], v[170:173], v[190:193], v[104:107]
	v_mfma_f32_16x16x32_bf16 v[100:103], v[178:181], v[190:193], v[100:103]
	v_mfma_f32_16x16x32_bf16 v[88:91], v[170:173], v[202:205], v[88:91]
	v_mfma_f32_16x16x32_bf16 v[84:87], v[178:181], v[202:205], v[84:87]
	v_mfma_f32_16x16x32_bf16 v[72:75], v[170:173], v[206:209], v[72:75]
	v_mfma_f32_16x16x32_bf16 v[68:71], v[178:181], v[206:209], v[68:71]
	v_mfma_f32_16x16x32_bf16 v[120:123], v[174:177], v[194:197], v[120:123]
	v_mfma_f32_16x16x32_bf16 v[116:119], v[182:185], v[194:197], v[116:119]
	v_mfma_f32_16x16x32_bf16 v[104:107], v[174:177], v[198:201], v[104:107]
	v_mfma_f32_16x16x32_bf16 v[100:103], v[182:185], v[198:201], v[100:103]
	v_mfma_f32_16x16x32_bf16 v[88:91], v[174:177], v[210:213], v[88:91]
	v_mfma_f32_16x16x32_bf16 v[84:87], v[182:185], v[210:213], v[84:87]
	v_mfma_f32_16x16x32_bf16 v[72:75], v[174:177], v[214:217], v[72:75]
	v_mfma_f32_16x16x32_bf16 v[68:71], v[182:185], v[214:217], v[68:71]
	s_barrier
	v_lshl_add_u64 v[166:167], s[78:79], 0, v[132:133]
	s_add_i32 s78, s64, s34
	s_mov_b32 m0, s78
	ds_read_b128 v[186:189], v145 offset:16384
	ds_read_b128 v[190:193], v145 offset:18432
	ds_read_b128 v[194:197], v146 offset:16384
	ds_read_b128 v[198:201], v146 offset:18432
	ds_read_b128 v[202:205], v145 offset:20480
	ds_read_b128 v[206:209], v145 offset:22528
	ds_read_b128 v[210:213], v146 offset:20480
	ds_read_b128 v[214:217], v146 offset:22528
	global_load_lds_dwordx4 v[166:167], off
	v_lshl_add_u64 v[218:219], v[166:167], 0, s[10:11]
	s_add_i32 m0, s78, 0x2000
	s_add_i32 s78, s66, s34
	global_load_lds_dwordx4 v[218:219], off
	v_lshl_add_u64 v[218:219], v[166:167], 0, s[14:15]
	s_mov_b32 m0, s78
	s_nop 0
	global_load_lds_dwordx4 v[218:219], off
	v_lshl_add_u64 v[218:219], v[166:167], 0, s[16:17]
	s_add_i32 m0, s78, 0x2000
	s_nop 0
	global_load_lds_dwordx4 v[218:219], off
	s_waitcnt vmcnt(4)
	s_waitcnt lgkmcnt(0)
	s_barrier
	v_mfma_f32_16x16x32_bf16 v[64:67], v[148:151], v[186:189], v[64:67]
	v_mfma_f32_16x16x32_bf16 v[60:63], v[158:161], v[186:189], v[60:63]
	v_mfma_f32_16x16x32_bf16 v[48:51], v[148:151], v[190:193], v[48:51]
	v_mfma_f32_16x16x32_bf16 v[44:47], v[158:161], v[190:193], v[44:47]
	v_mfma_f32_16x16x32_bf16 v[32:35], v[148:151], v[202:205], v[32:35]
	v_mfma_f32_16x16x32_bf16 v[28:31], v[158:161], v[202:205], v[28:31]
	v_mfma_f32_16x16x32_bf16 v[16:19], v[148:151], v[206:209], v[16:19]
	v_mfma_f32_16x16x32_bf16 v[12:15], v[158:161], v[206:209], v[12:15]
	v_mfma_f32_16x16x32_bf16 v[64:67], v[152:155], v[194:197], v[64:67]
	v_mfma_f32_16x16x32_bf16 v[60:63], v[162:165], v[194:197], v[60:63]
	v_mfma_f32_16x16x32_bf16 v[48:51], v[152:155], v[198:201], v[48:51]
	v_mfma_f32_16x16x32_bf16 v[44:47], v[162:165], v[198:201], v[44:47]
	v_mfma_f32_16x16x32_bf16 v[32:35], v[152:155], v[210:213], v[32:35]
	v_mfma_f32_16x16x32_bf16 v[28:31], v[162:165], v[210:213], v[28:31]
	v_mfma_f32_16x16x32_bf16 v[16:19], v[152:155], v[214:217], v[16:19]
	v_mfma_f32_16x16x32_bf16 v[12:15], v[162:165], v[214:217], v[12:15]
	v_mfma_f32_16x16x32_bf16 v[56:59], v[170:173], v[186:189], v[56:59]
	v_mfma_f32_16x16x32_bf16 v[52:55], v[178:181], v[186:189], v[52:55]
	v_mfma_f32_16x16x32_bf16 v[40:43], v[170:173], v[190:193], v[40:43]
	v_mfma_f32_16x16x32_bf16 v[36:39], v[178:181], v[190:193], v[36:39]
	v_mfma_f32_16x16x32_bf16 v[24:27], v[170:173], v[202:205], v[24:27]
	v_mfma_f32_16x16x32_bf16 v[20:23], v[178:181], v[202:205], v[20:23]
	v_mfma_f32_16x16x32_bf16 v[8:11], v[170:173], v[206:209], v[8:11]
	v_mfma_f32_16x16x32_bf16 v[4:7], v[178:181], v[206:209], v[4:7]
	v_mfma_f32_16x16x32_bf16 v[56:59], v[174:177], v[194:197], v[56:59]
	v_mfma_f32_16x16x32_bf16 v[52:55], v[182:185], v[194:197], v[52:55]
	v_mfma_f32_16x16x32_bf16 v[40:43], v[174:177], v[198:201], v[40:43]
	v_mfma_f32_16x16x32_bf16 v[36:39], v[182:185], v[198:201], v[36:39]
	v_mfma_f32_16x16x32_bf16 v[24:27], v[174:177], v[210:213], v[24:27]
	v_mfma_f32_16x16x32_bf16 v[20:23], v[182:185], v[210:213], v[20:23]
	v_mfma_f32_16x16x32_bf16 v[8:11], v[174:177], v[214:217], v[8:11]
	v_mfma_f32_16x16x32_bf16 v[4:7], v[182:185], v[214:217], v[4:7]
	s_barrier
	v_add_u32_e32 v147, s70, v143
	v_add_u32_e32 v152, s70, v144
	ds_read_b128 v[148:151], v147
	ds_read_b128 v[152:155], v152
	v_add_u32_e32 v147, s68, v143
	v_add_u32_e32 v162, s68, v144
	ds_read_b128 v[158:161], v147
	ds_read_b128 v[162:165], v162
	v_add_u32_e32 v147, s71, v143
	v_add_u32_e32 v169, s71, v144
	ds_read_b128 v[170:173], v147
	ds_read_b128 v[174:177], v169
	v_add_u32_e32 v147, s69, v143
	v_add_u32_e32 v169, s69, v144
	ds_read_b128 v[178:181], v147
	ds_read_b128 v[182:185], v169
	s_mov_b32 m0, s35
	v_lshl_add_u64 v[218:219], s[58:59], 0, v[0:1]
	ds_read_b128 v[186:189], v145 offset:32768
	ds_read_b128 v[190:193], v145 offset:34816
	ds_read_b128 v[194:197], v146 offset:32768
	ds_read_b128 v[198:201], v146 offset:34816
	ds_read_b128 v[202:205], v145 offset:36864
	ds_read_b128 v[206:209], v145 offset:38912
	ds_read_b128 v[210:213], v146 offset:36864
	ds_read_b128 v[214:217], v146 offset:38912
	global_load_lds_dwordx4 v[218:219], off
	v_lshl_add_u64 v[220:221], v[218:219], 0, s[20:21]
	s_mov_b32 m0, s39
	s_nop 0
	global_load_lds_dwordx4 v[220:221], off
	v_lshl_add_u64 v[220:221], v[218:219], 0, s[10:11]
	s_mov_b32 m0, s60
	v_lshl_add_u64 v[218:219], v[218:219], 0, s[22:23]
	global_load_lds_dwordx4 v[220:221], off
	s_mov_b32 m0, s61
	s_nop 0
	global_load_lds_dwordx4 v[218:219], off
	s_waitcnt vmcnt(8)
	s_waitcnt lgkmcnt(0)
	s_barrier
	v_mfma_f32_16x16x32_bf16 v[128:131], v[148:151], v[186:189], v[128:131]
	v_mfma_f32_16x16x32_bf16 v[124:127], v[158:161], v[186:189], v[124:127]
	v_mfma_f32_16x16x32_bf16 v[112:115], v[148:151], v[190:193], v[112:115]
	v_mfma_f32_16x16x32_bf16 v[108:111], v[158:161], v[190:193], v[108:111]
	v_mfma_f32_16x16x32_bf16 v[96:99], v[148:151], v[202:205], v[96:99]
	v_mfma_f32_16x16x32_bf16 v[92:95], v[158:161], v[202:205], v[92:95]
	v_mfma_f32_16x16x32_bf16 v[80:83], v[148:151], v[206:209], v[80:83]
	v_mfma_f32_16x16x32_bf16 v[76:79], v[158:161], v[206:209], v[76:79]
	v_mfma_f32_16x16x32_bf16 v[128:131], v[152:155], v[194:197], v[128:131]
	v_mfma_f32_16x16x32_bf16 v[124:127], v[162:165], v[194:197], v[124:127]
	v_mfma_f32_16x16x32_bf16 v[112:115], v[152:155], v[198:201], v[112:115]
	v_mfma_f32_16x16x32_bf16 v[108:111], v[162:165], v[198:201], v[108:111]
	v_mfma_f32_16x16x32_bf16 v[96:99], v[152:155], v[210:213], v[96:99]
	v_mfma_f32_16x16x32_bf16 v[92:95], v[162:165], v[210:213], v[92:95]
	v_mfma_f32_16x16x32_bf16 v[80:83], v[152:155], v[214:217], v[80:83]
	v_mfma_f32_16x16x32_bf16 v[76:79], v[162:165], v[214:217], v[76:79]
	v_mfma_f32_16x16x32_bf16 v[120:123], v[170:173], v[186:189], v[120:123]
	v_mfma_f32_16x16x32_bf16 v[116:119], v[178:181], v[186:189], v[116:119]
	v_mfma_f32_16x16x32_bf16 v[104:107], v[170:173], v[190:193], v[104:107]
	v_mfma_f32_16x16x32_bf16 v[100:103], v[178:181], v[190:193], v[100:103]
	v_mfma_f32_16x16x32_bf16 v[88:91], v[170:173], v[202:205], v[88:91]
	v_mfma_f32_16x16x32_bf16 v[84:87], v[178:181], v[202:205], v[84:87]
	v_mfma_f32_16x16x32_bf16 v[72:75], v[170:173], v[206:209], v[72:75]
	v_mfma_f32_16x16x32_bf16 v[68:71], v[178:181], v[206:209], v[68:71]
	v_mfma_f32_16x16x32_bf16 v[120:123], v[174:177], v[194:197], v[120:123]
	v_mfma_f32_16x16x32_bf16 v[116:119], v[182:185], v[194:197], v[116:119]
	v_mfma_f32_16x16x32_bf16 v[104:107], v[174:177], v[198:201], v[104:107]
	v_mfma_f32_16x16x32_bf16 v[100:103], v[182:185], v[198:201], v[100:103]
	v_mfma_f32_16x16x32_bf16 v[88:91], v[174:177], v[210:213], v[88:91]
	v_mfma_f32_16x16x32_bf16 v[84:87], v[182:185], v[210:213], v[84:87]
	v_mfma_f32_16x16x32_bf16 v[72:75], v[174:177], v[214:217], v[72:75]
	v_mfma_f32_16x16x32_bf16 v[68:71], v[182:185], v[214:217], v[68:71]
	s_barrier
	s_add_i32 s58, s70, s34
	v_lshl_add_u64 v[218:219], v[166:167], 0, s[24:25]
	s_mov_b32 m0, s58
	ds_read_b128 v[186:189], v145 offset:49152
	ds_read_b128 v[190:193], v145 offset:51200
	ds_read_b128 v[194:197], v146 offset:49152
	ds_read_b128 v[198:201], v146 offset:51200
	ds_read_b128 v[202:205], v145 offset:53248
	ds_read_b128 v[206:209], v145 offset:55296
	ds_read_b128 v[210:213], v146 offset:53248
	ds_read_b128 v[214:217], v146 offset:55296
	global_load_lds_dwordx4 v[218:219], off
	v_lshl_add_u64 v[218:219], v[166:167], 0, s[28:29]
	s_add_i32 m0, s58, 0x2000
	s_add_i32 s58, s71, s34
	global_load_lds_dwordx4 v[218:219], off
	v_lshl_add_u64 v[218:219], v[166:167], 0, s[36:37]
	s_mov_b32 m0, s58
	v_lshl_add_u64 v[166:167], v[166:167], 0, s[40:41]
	global_load_lds_dwordx4 v[218:219], off
	s_add_i32 m0, s58, 0x2000
	s_nop 0
	global_load_lds_dwordx4 v[166:167], off
	s_waitcnt vmcnt(4)
	s_waitcnt lgkmcnt(0)
	s_barrier
	v_mfma_f32_16x16x32_bf16 v[64:67], v[148:151], v[186:189], v[64:67]
	v_mfma_f32_16x16x32_bf16 v[60:63], v[158:161], v[186:189], v[60:63]
	v_mfma_f32_16x16x32_bf16 v[48:51], v[148:151], v[190:193], v[48:51]
	v_mfma_f32_16x16x32_bf16 v[44:47], v[158:161], v[190:193], v[44:47]
	v_mfma_f32_16x16x32_bf16 v[32:35], v[148:151], v[202:205], v[32:35]
	v_mfma_f32_16x16x32_bf16 v[28:31], v[158:161], v[202:205], v[28:31]
	v_mfma_f32_16x16x32_bf16 v[16:19], v[148:151], v[206:209], v[16:19]
	v_mfma_f32_16x16x32_bf16 v[12:15], v[158:161], v[206:209], v[12:15]
	v_mfma_f32_16x16x32_bf16 v[64:67], v[152:155], v[194:197], v[64:67]
	v_mfma_f32_16x16x32_bf16 v[60:63], v[162:165], v[194:197], v[60:63]
	v_mfma_f32_16x16x32_bf16 v[48:51], v[152:155], v[198:201], v[48:51]
	v_mfma_f32_16x16x32_bf16 v[44:47], v[162:165], v[198:201], v[44:47]
	v_mfma_f32_16x16x32_bf16 v[32:35], v[152:155], v[210:213], v[32:35]
	v_mfma_f32_16x16x32_bf16 v[28:31], v[162:165], v[210:213], v[28:31]
	v_mfma_f32_16x16x32_bf16 v[16:19], v[152:155], v[214:217], v[16:19]
	v_mfma_f32_16x16x32_bf16 v[12:15], v[162:165], v[214:217], v[12:15]
	v_mfma_f32_16x16x32_bf16 v[56:59], v[170:173], v[186:189], v[56:59]
	v_mfma_f32_16x16x32_bf16 v[52:55], v[178:181], v[186:189], v[52:55]
	v_mfma_f32_16x16x32_bf16 v[40:43], v[170:173], v[190:193], v[40:43]
	v_mfma_f32_16x16x32_bf16 v[36:39], v[178:181], v[190:193], v[36:39]
	v_mfma_f32_16x16x32_bf16 v[24:27], v[170:173], v[202:205], v[24:27]
	v_mfma_f32_16x16x32_bf16 v[20:23], v[178:181], v[202:205], v[20:23]
	v_mfma_f32_16x16x32_bf16 v[8:11], v[170:173], v[206:209], v[8:11]
	v_mfma_f32_16x16x32_bf16 v[4:7], v[178:181], v[206:209], v[4:7]
	v_mfma_f32_16x16x32_bf16 v[56:59], v[174:177], v[194:197], v[56:59]
	v_mfma_f32_16x16x32_bf16 v[52:55], v[182:185], v[194:197], v[52:55]
	v_mfma_f32_16x16x32_bf16 v[40:43], v[174:177], v[198:201], v[40:43]
	v_mfma_f32_16x16x32_bf16 v[36:39], v[182:185], v[198:201], v[36:39]
	v_mfma_f32_16x16x32_bf16 v[24:27], v[174:177], v[210:213], v[24:27]
	v_mfma_f32_16x16x32_bf16 v[20:23], v[182:185], v[210:213], v[20:23]
	v_mfma_f32_16x16x32_bf16 v[8:11], v[174:177], v[214:217], v[8:11]
	v_mfma_f32_16x16x32_bf16 v[4:7], v[182:185], v[214:217], v[4:7]
	s_add_i32 s77, s77, 2
	s_add_u32 s56, s56, 0x100
	s_addc_u32 s57, s57, 0
	s_cmp_gt_u32 s77, 61
	s_barrier
	s_cbranch_scc0 .LBB0_1371
	s_add_u32 s56, s53, 0xffffff00
	s_addc_u32 s57, s72, -1
	s_andn2_b64 vcc, exec, s[6:7]
	s_cbranch_vccnz .LBB0_1362
	v_mov_b32_e32 v4, 0
	s_mov_b32 s0, s48
	s_mov_b32 s8, s50
	s_mov_b64 s[18:19], s[54:55]
	s_mov_b32 s63, s52
	v_mov_b32_e32 v5, v4
	v_mov_b32_e32 v6, v4
	v_mov_b32_e32 v7, v4
	v_mov_b32_e32 v8, v4
	v_mov_b32_e32 v9, v4
	v_mov_b32_e32 v10, v4
	v_mov_b32_e32 v11, v4
	v_mov_b32_e32 v20, v4
	v_mov_b32_e32 v21, v4
	v_mov_b32_e32 v22, v4
	v_mov_b32_e32 v23, v4
	v_mov_b32_e32 v24, v4
	v_mov_b32_e32 v25, v4
	v_mov_b32_e32 v26, v4
	v_mov_b32_e32 v27, v4
	v_mov_b32_e32 v36, v4
	v_mov_b32_e32 v37, v4
	v_mov_b32_e32 v38, v4
	v_mov_b32_e32 v39, v4
	v_mov_b32_e32 v40, v4
	v_mov_b32_e32 v41, v4
	v_mov_b32_e32 v42, v4
	v_mov_b32_e32 v43, v4
	v_mov_b32_e32 v52, v4
	v_mov_b32_e32 v53, v4
	v_mov_b32_e32 v54, v4
	v_mov_b32_e32 v55, v4
	v_mov_b32_e32 v56, v4
	v_mov_b32_e32 v57, v4
	v_mov_b32_e32 v58, v4
	v_mov_b32_e32 v59, v4
	v_mov_b32_e32 v12, v4
	v_mov_b32_e32 v13, v4
	v_mov_b32_e32 v14, v4
	v_mov_b32_e32 v15, v4
	v_mov_b32_e32 v16, v4
	v_mov_b32_e32 v17, v4
	v_mov_b32_e32 v18, v4
	v_mov_b32_e32 v19, v4
	v_mov_b32_e32 v28, v4
	v_mov_b32_e32 v29, v4
	v_mov_b32_e32 v30, v4
	v_mov_b32_e32 v31, v4
	v_mov_b32_e32 v32, v4
	v_mov_b32_e32 v33, v4
	v_mov_b32_e32 v34, v4
	v_mov_b32_e32 v35, v4
	v_mov_b32_e32 v44, v4
	v_mov_b32_e32 v45, v4
	v_mov_b32_e32 v46, v4
	v_mov_b32_e32 v47, v4
	v_mov_b32_e32 v48, v4
	v_mov_b32_e32 v49, v4
	v_mov_b32_e32 v50, v4
	v_mov_b32_e32 v51, v4
	v_mov_b32_e32 v60, v4
	v_mov_b32_e32 v61, v4
	v_mov_b32_e32 v62, v4
	v_mov_b32_e32 v63, v4
	v_mov_b32_e32 v64, v4
	v_mov_b32_e32 v65, v4
	v_mov_b32_e32 v66, v4
	v_mov_b32_e32 v67, v4
	v_mov_b32_e32 v68, v4
	v_mov_b32_e32 v69, v4
	v_mov_b32_e32 v70, v4
	v_mov_b32_e32 v71, v4
	v_mov_b32_e32 v72, v4
	v_mov_b32_e32 v73, v4
	v_mov_b32_e32 v74, v4
	v_mov_b32_e32 v75, v4
	v_mov_b32_e32 v84, v4
	v_mov_b32_e32 v85, v4
	v_mov_b32_e32 v86, v4
	v_mov_b32_e32 v87, v4
	v_mov_b32_e32 v88, v4
	v_mov_b32_e32 v89, v4
	v_mov_b32_e32 v90, v4
	v_mov_b32_e32 v91, v4
	v_mov_b32_e32 v100, v4
	v_mov_b32_e32 v101, v4
	v_mov_b32_e32 v102, v4
	v_mov_b32_e32 v103, v4
	v_mov_b32_e32 v104, v4
	v_mov_b32_e32 v105, v4
	v_mov_b32_e32 v106, v4
	v_mov_b32_e32 v107, v4
	v_mov_b32_e32 v116, v4
	v_mov_b32_e32 v117, v4
	v_mov_b32_e32 v118, v4
	v_mov_b32_e32 v119, v4
	v_mov_b32_e32 v120, v4
	v_mov_b32_e32 v121, v4
	v_mov_b32_e32 v122, v4
	v_mov_b32_e32 v123, v4
	v_mov_b32_e32 v76, v4
	v_mov_b32_e32 v77, v4
	v_mov_b32_e32 v78, v4
	v_mov_b32_e32 v79, v4
	v_mov_b32_e32 v80, v4
	v_mov_b32_e32 v81, v4
	v_mov_b32_e32 v82, v4
	v_mov_b32_e32 v83, v4
	v_mov_b32_e32 v92, v4
	v_mov_b32_e32 v93, v4
	v_mov_b32_e32 v94, v4
	v_mov_b32_e32 v95, v4
	v_mov_b32_e32 v96, v4
	v_mov_b32_e32 v97, v4
	v_mov_b32_e32 v98, v4
	v_mov_b32_e32 v99, v4
	v_mov_b32_e32 v108, v4
	v_mov_b32_e32 v109, v4
	v_mov_b32_e32 v110, v4
	v_mov_b32_e32 v111, v4
	v_mov_b32_e32 v112, v4
	v_mov_b32_e32 v113, v4
	v_mov_b32_e32 v114, v4
	v_mov_b32_e32 v115, v4
	v_mov_b32_e32 v124, v4
	v_mov_b32_e32 v125, v4
	v_mov_b32_e32 v126, v4
	v_mov_b32_e32 v127, v4
	v_mov_b32_e32 v128, v4
	v_mov_b32_e32 v129, v4
	v_mov_b32_e32 v130, v4
	v_mov_b32_e32 v131, v4
	s_andn2_b64 vcc, exec, s[4:5]
	s_cbranch_vccnz .LBB0_1363
